# baseline (speedup 1.0000x reference)
; #define WAIT_L(n) asm volatile("s_waitcnt lgkmcnt(" #n ")" ::: "memory")
; #define BAR __builtin_amdgcn_s_barrier()
; #define SCHED __builtin_amdgcn_sched_barrier(0)
; template <int MODE>
; __device__ __forceinline__ void gemm_tile(const int ph, const int which, const int pm, const int pn) {
;     ...
;     LDB(B0, 0, 0); SCHED; LDA(At, 0, 0); STAGE(SA(1, 1), RA, brow + HALF, t + 1);
;     WAIT_L(8); BAR; WAIT_L(0); MMA(0, 0, At, B0); BAR; SCHED;
;     LDB(B1, 0, 1); STAGE(SB(0, 0), RB, bcol, t + 2);
;     BAR; WAIT_L(0); MMA(0, 1, At, B1); BAR;
;     LDA(At, 0, 1); STAGE(SA(0, 0), RA, brow, t + 2);
;     BAR; WAIT_L(0); MMA(1, 0, At, B0); BAR; SCHED;
.LBB0_131:
	ds_read_b128 v[160:163], v158
	ds_read_b128 v[164:167], v158 offset:1024
	ds_read_b128 v[168:171], v158 offset:2048
	ds_read_b128 v[172:175], v158 offset:3072
	s_add_i32 s12, s16, s25
	v_readfirstlane_b32 s28, v155
	s_add_i32 s13, s12, 0x80
	s_mov_b32 m0, s28
	ds_read_b128 v[176:179], v137
	ds_read_b128 v[180:183], v137 offset:1024
	ds_read_b128 v[184:187], v136
	ds_read_b128 v[188:191], v136 offset:1024
	ds_read_b128 v[192:195], v135
	ds_read_b128 v[196:199], v135 offset:1024
	ds_read_b128 v[200:203], v134
	ds_read_b128 v[204:207], v134 offset:1024
	buffer_load_dwordx4 v138, s[4:7], s13 offen lds
	s_add_i32 s13, s3, s25
	v_readfirstlane_b32 s29, v153
	s_add_i32 s28, s13, 0x80
	s_mov_b32 m0, s29
	s_nop 0
	buffer_load_dwordx4 v138, s[4:7], s28 offen lds
	s_waitcnt lgkmcnt(8)
	s_barrier
	s_waitcnt lgkmcnt(0)
	s_setprio 1
	v_mfma_f32_16x16x32_bf16 v[126:129], v[160:163], v[176:179], v[126:129]
	v_mfma_f32_16x16x32_bf16 v[122:125], v[168:171], v[176:179], v[122:125]
	v_mfma_f32_16x16x32_bf16 v[118:121], v[160:163], v[184:187], v[118:121]
	v_mfma_f32_16x16x32_bf16 v[114:117], v[168:171], v[184:187], v[114:117]
	v_mfma_f32_16x16x32_bf16 v[110:113], v[160:163], v[192:195], v[110:113]
	v_mfma_f32_16x16x32_bf16 v[106:109], v[168:171], v[192:195], v[106:109]
	v_mfma_f32_16x16x32_bf16 v[102:105], v[160:163], v[200:203], v[102:105]
	v_mfma_f32_16x16x32_bf16 v[98:101], v[168:171], v[200:203], v[98:101]
	v_mfma_f32_16x16x32_bf16 v[126:129], v[164:167], v[180:183], v[126:129]
	v_mfma_f32_16x16x32_bf16 v[122:125], v[172:175], v[180:183], v[122:125]
	v_mfma_f32_16x16x32_bf16 v[118:121], v[164:167], v[188:191], v[118:121]
	v_mfma_f32_16x16x32_bf16 v[114:117], v[172:175], v[188:191], v[114:117]
	v_mfma_f32_16x16x32_bf16 v[110:113], v[164:167], v[196:199], v[110:113]
	v_mfma_f32_16x16x32_bf16 v[106:109], v[172:175], v[196:199], v[106:109]
	v_mfma_f32_16x16x32_bf16 v[102:105], v[164:167], v[204:207], v[102:105]
	v_mfma_f32_16x16x32_bf16 v[98:101], v[172:175], v[204:207], v[98:101]
	s_setprio 0
	s_barrier
	s_add_i32 s28, s24, s25
	v_readfirstlane_b32 s38, v141
	s_add_i32 s29, s28, 0x100
	s_mov_b32 m0, s38
	ds_read_b128 v[236:239], v157
	ds_read_b128 v[240:243], v157 offset:1024
	ds_read_b128 v[244:247], v157 offset:2048
	ds_read_b128 v[248:251], v157 offset:3072
	buffer_load_dwordx4 v138, s[68:71], s29 offen lds
	s_add_i32 s29, s23, s25
	v_readfirstlane_b32 s43, v142
	s_add_i32 s38, s29, 0x100
	s_mov_b32 m0, s43
	s_add_i32 s27, s27, 2
	buffer_load_dwordx4 v138, s[68:71], s38 offen lds
	s_barrier
	s_waitcnt lgkmcnt(0)
	s_setprio 1
	v_mfma_f32_16x16x32_bf16 v[94:97], v[236:239], v[176:179], v[94:97]
	v_mfma_f32_16x16x32_bf16 v[90:93], v[244:247], v[176:179], v[90:93]
	v_mfma_f32_16x16x32_bf16 v[86:89], v[236:239], v[184:187], v[86:89]
	v_mfma_f32_16x16x32_bf16 v[82:85], v[244:247], v[184:187], v[82:85]
	v_mfma_f32_16x16x32_bf16 v[78:81], v[236:239], v[192:195], v[78:81]
	v_mfma_f32_16x16x32_bf16 v[74:77], v[244:247], v[192:195], v[74:77]
	v_mfma_f32_16x16x32_bf16 v[70:73], v[236:239], v[200:203], v[70:73]
	v_mfma_f32_16x16x32_bf16 v[66:69], v[244:247], v[200:203], v[66:69]
	v_mfma_f32_16x16x32_bf16 v[94:97], v[240:243], v[180:183], v[94:97]
	v_mfma_f32_16x16x32_bf16 v[90:93], v[248:251], v[180:183], v[90:93]
	v_mfma_f32_16x16x32_bf16 v[86:89], v[240:243], v[188:191], v[86:89]
	v_mfma_f32_16x16x32_bf16 v[82:85], v[248:251], v[188:191], v[82:85]
	v_mfma_f32_16x16x32_bf16 v[78:81], v[240:243], v[196:199], v[78:81]
	v_mfma_f32_16x16x32_bf16 v[74:77], v[248:251], v[196:199], v[74:77]
	v_mfma_f32_16x16x32_bf16 v[70:73], v[240:243], v[204:207], v[70:73]
	v_mfma_f32_16x16x32_bf16 v[66:69], v[248:251], v[204:207], v[66:69]
	s_setprio 0
	s_add_i32 s38, s22, s25
	v_readfirstlane_b32 s50, v139
	s_add_i32 s43, s38, 0x100
	s_mov_b32 m0, s50
	s_barrier
	ds_read_b128 v[176:179], v137 offset:16384
	ds_read_b128 v[180:183], v137 offset:17408
	ds_read_b128 v[184:187], v136 offset:16384
	ds_read_b128 v[188:191], v136 offset:17408
	ds_read_b128 v[192:195], v135 offset:16384
	ds_read_b128 v[196:199], v135 offset:17408
	ds_read_b128 v[200:203], v134 offset:16384
	ds_read_b128 v[204:207], v134 offset:17408
	buffer_load_dwordx4 v138, s[4:7], s43 offen lds
	s_add_i32 s43, s19, s25
	v_readfirstlane_b32 s51, v143
	s_add_i32 s50, s43, 0x100
	s_mov_b32 m0, s51
	s_nop 0
	buffer_load_dwordx4 v138, s[4:7], s50 offen lds
	s_barrier
	s_waitcnt lgkmcnt(0)
	s_setprio 1
	v_mfma_f32_16x16x32_bf16 v[62:65], v[160:163], v[176:179], v[62:65]
	v_mfma_f32_16x16x32_bf16 v[58:61], v[168:171], v[176:179], v[58:61]
	v_mfma_f32_16x16x32_bf16 v[54:57], v[160:163], v[184:187], v[54:57]
	v_mfma_f32_16x16x32_bf16 v[50:53], v[168:171], v[184:187], v[50:53]
	v_mfma_f32_16x16x32_bf16 v[46:49], v[160:163], v[192:195], v[46:49]
	v_mfma_f32_16x16x32_bf16 v[42:45], v[168:171], v[192:195], v[42:45]
	v_mfma_f32_16x16x32_bf16 v[38:41], v[160:163], v[200:203], v[38:41]
	v_mfma_f32_16x16x32_bf16 v[34:37], v[168:171], v[200:203], v[34:37]
	v_mfma_f32_16x16x32_bf16 v[62:65], v[164:167], v[180:183], v[62:65]
	v_mfma_f32_16x16x32_bf16 v[58:61], v[172:175], v[180:183], v[58:61]
	v_mfma_f32_16x16x32_bf16 v[54:57], v[164:167], v[188:191], v[54:57]
	v_mfma_f32_16x16x32_bf16 v[50:53], v[172:175], v[188:191], v[50:53]
	v_mfma_f32_16x16x32_bf16 v[46:49], v[164:167], v[196:199], v[46:49]
	v_mfma_f32_16x16x32_bf16 v[42:45], v[172:175], v[196:199], v[42:45]
	v_mfma_f32_16x16x32_bf16 v[38:41], v[164:167], v[204:207], v[38:41]
	v_mfma_f32_16x16x32_bf16 v[34:37], v[172:175], v[204:207], v[34:37]
	s_setprio 0
	s_barrier
; #define WAIT_V(n) asm volatile("s_waitcnt vmcnt(" #n ")" ::: "memory")
; #define WAIT_L(n) asm volatile("s_waitcnt lgkmcnt(" #n ")" ::: "memory")
; #define BAR __builtin_amdgcn_s_barrier()
; #define SCHED __builtin_amdgcn_sched_barrier(0)
; template <int MODE>
; __device__ __forceinline__ void gemm_tile(const int ph, const int which, const int pm, const int pn) {
;     ...
;     STAGE(SB(0, 1), RB, bcolB, t + 2);
;     WAIT_V(6); BAR; MMA(1, 1, At, B1); BAR;
;     LDB(B0, 1, 0); SCHED; LDA(At, 1, 0); STAGE(SA(0, 1), RA, brow + HALF, t + 2);
;     WAIT_L(8); BAR; WAIT_L(0); MMA(0, 0, At, B0); BAR; SCHED;
;     LDB(B1, 1, 1); STAGE(SB(1, 0), RB, bcol, t + 3);
;     BAR; WAIT_L(0); MMA(0, 1, At, B1); BAR;
;     LDA(At, 1, 1); STAGE(SA(1, 0), RA, brow, t + 3);
	s_add_i32 s50, s18, s25
	v_readfirstlane_b32 s72, v144
	s_add_i32 s51, s50, 0x100
	s_mov_b32 m0, s72
	v_readfirstlane_b32 s73, v145
	buffer_load_dwordx4 v138, s[68:71], s51 offen lds
	s_add_i32 s51, s17, s25
	s_add_i32 s72, s51, 0x100
	s_mov_b32 m0, s73
	s_nop 0
	buffer_load_dwordx4 v138, s[68:71], s72 offen lds
	s_waitcnt vmcnt(6)
	s_barrier
	s_setprio 1
	v_mfma_f32_16x16x32_bf16 v[30:33], v[236:239], v[176:179], v[30:33]
	v_mfma_f32_16x16x32_bf16 v[26:29], v[244:247], v[176:179], v[26:29]
	v_mfma_f32_16x16x32_bf16 v[22:25], v[236:239], v[184:187], v[22:25]
	v_mfma_f32_16x16x32_bf16 v[18:21], v[244:247], v[184:187], v[18:21]
	v_mfma_f32_16x16x32_bf16 v[14:17], v[236:239], v[192:195], v[14:17]
	v_mfma_f32_16x16x32_bf16 v[10:13], v[244:247], v[192:195], v[10:13]
	v_mfma_f32_16x16x32_bf16 v[6:9], v[236:239], v[200:203], v[6:9]
	v_mfma_f32_16x16x32_bf16 v[2:5], v[244:247], v[200:203], v[2:5]
	v_mfma_f32_16x16x32_bf16 v[30:33], v[240:243], v[180:183], v[30:33]
	v_mfma_f32_16x16x32_bf16 v[26:29], v[248:251], v[180:183], v[26:29]
	v_mfma_f32_16x16x32_bf16 v[22:25], v[240:243], v[188:191], v[22:25]
	v_mfma_f32_16x16x32_bf16 v[18:21], v[248:251], v[188:191], v[18:21]
	v_mfma_f32_16x16x32_bf16 v[14:17], v[240:243], v[196:199], v[14:17]
	v_mfma_f32_16x16x32_bf16 v[10:13], v[248:251], v[196:199], v[10:13]
	v_mfma_f32_16x16x32_bf16 v[6:9], v[240:243], v[204:207], v[6:9]
	v_mfma_f32_16x16x32_bf16 v[2:5], v[248:251], v[204:207], v[2:5]
	s_setprio 0
	s_barrier
	ds_read_b128 v[160:163], v146
	ds_read_b128 v[164:167], v146 offset:1024
	ds_read_b128 v[168:171], v146 offset:2048
	ds_read_b128 v[172:175], v146 offset:3072
	v_readfirstlane_b32 s72, v147
	s_addk_i32 s12, 0x100
	s_mov_b32 m0, s72
	ds_read_b128 v[176:179], v137 offset:32768
	ds_read_b128 v[180:183], v137 offset:33792
	ds_read_b128 v[184:187], v136 offset:32768
	ds_read_b128 v[188:191], v136 offset:33792
	ds_read_b128 v[192:195], v135 offset:32768
	ds_read_b128 v[196:199], v135 offset:33792
	ds_read_b128 v[200:203], v134 offset:32768
	ds_read_b128 v[204:207], v134 offset:33792
	buffer_load_dwordx4 v138, s[4:7], s12 offen lds
	v_readfirstlane_b32 s12, v148
	s_addk_i32 s13, 0x100
	s_mov_b32 m0, s12
	s_nop 0
	buffer_load_dwordx4 v138, s[4:7], s13 offen lds
	s_waitcnt lgkmcnt(8)
	s_barrier
	s_waitcnt lgkmcnt(0)
	s_setprio 1
	v_mfma_f32_16x16x32_bf16 v[126:129], v[160:163], v[176:179], v[126:129]
	v_mfma_f32_16x16x32_bf16 v[122:125], v[168:171], v[176:179], v[122:125]
	v_mfma_f32_16x16x32_bf16 v[118:121], v[160:163], v[184:187], v[118:121]
	v_mfma_f32_16x16x32_bf16 v[114:117], v[168:171], v[184:187], v[114:117]
	v_mfma_f32_16x16x32_bf16 v[110:113], v[160:163], v[192:195], v[110:113]
	v_mfma_f32_16x16x32_bf16 v[106:109], v[168:171], v[192:195], v[106:109]
	v_mfma_f32_16x16x32_bf16 v[102:105], v[160:163], v[200:203], v[102:105]
	v_mfma_f32_16x16x32_bf16 v[98:101], v[168:171], v[200:203], v[98:101]
	v_mfma_f32_16x16x32_bf16 v[126:129], v[164:167], v[180:183], v[126:129]
	v_mfma_f32_16x16x32_bf16 v[122:125], v[172:175], v[180:183], v[122:125]
	v_mfma_f32_16x16x32_bf16 v[118:121], v[164:167], v[188:191], v[118:121]
	v_mfma_f32_16x16x32_bf16 v[114:117], v[172:175], v[188:191], v[114:117]
	v_mfma_f32_16x16x32_bf16 v[110:113], v[164:167], v[196:199], v[110:113]
	v_mfma_f32_16x16x32_bf16 v[106:109], v[172:175], v[196:199], v[106:109]
	v_mfma_f32_16x16x32_bf16 v[102:105], v[164:167], v[204:207], v[102:105]
	v_mfma_f32_16x16x32_bf16 v[98:101], v[172:175], v[204:207], v[98:101]
	s_setprio 0
	s_barrier
	v_readfirstlane_b32 s12, v149
	s_addk_i32 s28, 0x180
	s_mov_b32 m0, s12
	v_readfirstlane_b32 s12, v150
	ds_read_b128 v[236:239], v140
	ds_read_b128 v[240:243], v140 offset:1024
	ds_read_b128 v[244:247], v140 offset:2048
	ds_read_b128 v[248:251], v140 offset:3072
	buffer_load_dwordx4 v138, s[68:71], s28 offen lds
	s_addk_i32 s29, 0x180
	s_mov_b32 m0, s12
	s_nop 0
	buffer_load_dwordx4 v138, s[68:71], s29 offen lds
	s_barrier
	s_waitcnt lgkmcnt(0)
	s_setprio 1
	v_mfma_f32_16x16x32_bf16 v[94:97], v[236:239], v[176:179], v[94:97]
	v_mfma_f32_16x16x32_bf16 v[90:93], v[244:247], v[176:179], v[90:93]
	v_mfma_f32_16x16x32_bf16 v[86:89], v[236:239], v[184:187], v[86:89]
	v_mfma_f32_16x16x32_bf16 v[82:85], v[244:247], v[184:187], v[82:85]
	v_mfma_f32_16x16x32_bf16 v[78:81], v[236:239], v[192:195], v[78:81]
	v_mfma_f32_16x16x32_bf16 v[74:77], v[244:247], v[192:195], v[74:77]
	v_mfma_f32_16x16x32_bf16 v[70:73], v[236:239], v[200:203], v[70:73]
	v_mfma_f32_16x16x32_bf16 v[66:69], v[244:247], v[200:203], v[66:69]
	v_mfma_f32_16x16x32_bf16 v[94:97], v[240:243], v[180:183], v[94:97]
	v_mfma_f32_16x16x32_bf16 v[90:93], v[248:251], v[180:183], v[90:93]
	v_mfma_f32_16x16x32_bf16 v[86:89], v[240:243], v[188:191], v[86:89]
	v_mfma_f32_16x16x32_bf16 v[82:85], v[248:251], v[188:191], v[82:85]
	v_mfma_f32_16x16x32_bf16 v[78:81], v[240:243], v[196:199], v[78:81]
	v_mfma_f32_16x16x32_bf16 v[74:77], v[248:251], v[196:199], v[74:77]
	v_mfma_f32_16x16x32_bf16 v[70:73], v[240:243], v[204:207], v[70:73]
	v_mfma_f32_16x16x32_bf16 v[66:69], v[248:251], v[204:207], v[66:69]
	s_setprio 0
	v_readfirstlane_b32 s12, v151
	s_addk_i32 s38, 0x180
	s_mov_b32 m0, s12
	v_readfirstlane_b32 s12, v152
	s_barrier
	ds_read_b128 v[176:179], v137 offset:49152
	ds_read_b128 v[180:183], v137 offset:50176
	ds_read_b128 v[184:187], v136 offset:49152
	ds_read_b128 v[188:191], v136 offset:50176
	ds_read_b128 v[192:195], v135 offset:49152
	ds_read_b128 v[196:199], v135 offset:50176
	ds_read_b128 v[200:203], v134 offset:49152
	ds_read_b128 v[204:207], v134 offset:50176
	buffer_load_dwordx4 v138, s[4:7], s38 offen lds
	s_addk_i32 s43, 0x180
	s_mov_b32 m0, s12
	s_nop 0
	buffer_load_dwordx4 v138, s[4:7], s43 offen lds
	s_barrier
; #define WAIT_V(n) asm volatile("s_waitcnt vmcnt(" #n ")" ::: "memory")
; #define WAIT_L(n) asm volatile("s_waitcnt lgkmcnt(" #n ")" ::: "memory")
; #define BAR __builtin_amdgcn_s_barrier()
; #define SCHED __builtin_amdgcn_sched_barrier(0)
; template <int MODE>
; __device__ __forceinline__ void gemm_tile(const int ph, const int which, const int pm, const int pn) {
;     ...
;     BAR; WAIT_L(0); MMA(1, 0, At, B0); BAR; SCHED;
;     STAGE(SB(1, 1), RB, bcolB, t + 3);
;     WAIT_V(6); BAR; MMA(1, 1, At, B1); BAR;
;   }
;   {
;     LDB(B0, 0, 0); LDA(At, 0, 0); STAGE(SA(1, 1), RA, brow + HALF, nt - 1);
;     BAR; WAIT_L(0); MMA(0, 0, At, B0); BAR;
;     LDB(B1, 0, 1); BAR; WAIT_L(0); MMA(0, 1, At, B1); BAR;
	s_waitcnt lgkmcnt(0)
	s_setprio 1
	v_mfma_f32_16x16x32_bf16 v[62:65], v[160:163], v[176:179], v[62:65]
	v_mfma_f32_16x16x32_bf16 v[58:61], v[168:171], v[176:179], v[58:61]
	v_mfma_f32_16x16x32_bf16 v[54:57], v[160:163], v[184:187], v[54:57]
	v_mfma_f32_16x16x32_bf16 v[50:53], v[168:171], v[184:187], v[50:53]
	v_mfma_f32_16x16x32_bf16 v[46:49], v[160:163], v[192:195], v[46:49]
	v_mfma_f32_16x16x32_bf16 v[42:45], v[168:171], v[192:195], v[42:45]
	v_mfma_f32_16x16x32_bf16 v[38:41], v[160:163], v[200:203], v[38:41]
	v_mfma_f32_16x16x32_bf16 v[34:37], v[168:171], v[200:203], v[34:37]
	v_mfma_f32_16x16x32_bf16 v[62:65], v[164:167], v[180:183], v[62:65]
	v_mfma_f32_16x16x32_bf16 v[58:61], v[172:175], v[180:183], v[58:61]
	v_mfma_f32_16x16x32_bf16 v[54:57], v[164:167], v[188:191], v[54:57]
	v_mfma_f32_16x16x32_bf16 v[50:53], v[172:175], v[188:191], v[50:53]
	v_mfma_f32_16x16x32_bf16 v[46:49], v[164:167], v[196:199], v[46:49]
	v_mfma_f32_16x16x32_bf16 v[42:45], v[172:175], v[196:199], v[42:45]
	v_mfma_f32_16x16x32_bf16 v[38:41], v[164:167], v[204:207], v[38:41]
	v_mfma_f32_16x16x32_bf16 v[34:37], v[172:175], v[204:207], v[34:37]
	s_setprio 0
	s_barrier
	v_readfirstlane_b32 s12, v154
	s_addk_i32 s50, 0x180
	s_mov_b32 m0, s12
	v_readfirstlane_b32 s12, v156
	buffer_load_dwordx4 v138, s[68:71], s50 offen lds
	s_addk_i32 s51, 0x180
	s_mov_b32 m0, s12
	s_nop 0
	buffer_load_dwordx4 v138, s[68:71], s51 offen lds
	s_waitcnt vmcnt(6)
	s_barrier
	s_setprio 1
	v_mfma_f32_16x16x32_bf16 v[30:33], v[236:239], v[176:179], v[30:33]
	v_mfma_f32_16x16x32_bf16 v[26:29], v[244:247], v[176:179], v[26:29]
	v_mfma_f32_16x16x32_bf16 v[22:25], v[236:239], v[184:187], v[22:25]
	v_mfma_f32_16x16x32_bf16 v[18:21], v[244:247], v[184:187], v[18:21]
	v_mfma_f32_16x16x32_bf16 v[14:17], v[236:239], v[192:195], v[14:17]
	v_mfma_f32_16x16x32_bf16 v[10:13], v[244:247], v[192:195], v[10:13]
	v_mfma_f32_16x16x32_bf16 v[6:9], v[236:239], v[200:203], v[6:9]
	v_mfma_f32_16x16x32_bf16 v[2:5], v[244:247], v[200:203], v[2:5]
	v_mfma_f32_16x16x32_bf16 v[30:33], v[240:243], v[180:183], v[30:33]
	v_mfma_f32_16x16x32_bf16 v[26:29], v[248:251], v[180:183], v[26:29]
	v_mfma_f32_16x16x32_bf16 v[22:25], v[240:243], v[188:191], v[22:25]
	v_mfma_f32_16x16x32_bf16 v[18:21], v[248:251], v[188:191], v[18:21]
	v_mfma_f32_16x16x32_bf16 v[14:17], v[240:243], v[196:199], v[14:17]
	v_mfma_f32_16x16x32_bf16 v[10:13], v[248:251], v[196:199], v[10:13]
	v_mfma_f32_16x16x32_bf16 v[6:9], v[240:243], v[204:207], v[6:9]
	v_mfma_f32_16x16x32_bf16 v[2:5], v[248:251], v[204:207], v[2:5]
	s_setprio 0
	s_addk_i32 s25, 0x100
	s_cmp_lt_u32 s27, s2
	s_barrier
	s_cbranch_scc1 .LBB0_131
	s_add_i32 s2, s26, s11
	s_lshl_b32 s2, s2, 1
	v_readfirstlane_b32 s3, v155
	s_addk_i32 s2, 0xff80
	s_mov_b32 s6, s70
	s_mov_b32 s7, s71
	s_mov_b32 m0, s3
	v_readfirstlane_b32 s3, v153
	ds_read_b128 v[142:145], v158
	ds_read_b128 v[148:151], v158 offset:1024
	ds_read_b128 v[160:163], v158 offset:2048
	ds_read_b128 v[164:167], v158 offset:3072
	ds_read_b128 v[168:171], v137
	ds_read_b128 v[172:175], v137 offset:1024
	ds_read_b128 v[176:179], v136
	ds_read_b128 v[180:183], v136 offset:1024
	ds_read_b128 v[184:187], v135
	ds_read_b128 v[188:191], v135 offset:1024
	ds_read_b128 v[192:195], v134
	ds_read_b128 v[196:199], v134 offset:1024
	buffer_load_dwordx4 v138, s[4:7], s2 offen lds
	s_add_i32 s2, s2, s10
	s_mov_b32 m0, s3
	s_nop 0
	buffer_load_dwordx4 v138, s[4:7], s2 offen lds
	s_barrier
	s_waitcnt lgkmcnt(0)
	s_setprio 1
	v_mfma_f32_16x16x32_bf16 v[126:129], v[142:145], v[168:171], v[126:129]
	v_mfma_f32_16x16x32_bf16 v[122:125], v[160:163], v[168:171], v[122:125]
	v_mfma_f32_16x16x32_bf16 v[118:121], v[142:145], v[176:179], v[118:121]
	v_mfma_f32_16x16x32_bf16 v[114:117], v[160:163], v[176:179], v[114:117]
	v_mfma_f32_16x16x32_bf16 v[102:105], v[142:145], v[192:195], v[102:105]
	v_mfma_f32_16x16x32_bf16 v[98:101], v[160:163], v[192:195], v[98:101]
	v_mfma_f32_16x16x32_bf16 v[126:129], v[148:151], v[172:175], v[126:129]
	v_mfma_f32_16x16x32_bf16 v[122:125], v[164:167], v[172:175], v[122:125]
	v_mfma_f32_16x16x32_bf16 v[118:121], v[148:151], v[180:183], v[118:121]
	v_mfma_f32_16x16x32_bf16 v[114:117], v[164:167], v[180:183], v[114:117]
	v_mfma_f32_16x16x32_bf16 v[110:113], v[142:145], v[184:187], v[110:113]
	v_mfma_f32_16x16x32_bf16 v[106:109], v[160:163], v[184:187], v[106:109]
	v_mfma_f32_16x16x32_bf16 v[102:105], v[148:151], v[196:199], v[102:105]
	v_mfma_f32_16x16x32_bf16 v[98:101], v[164:167], v[196:199], v[98:101]
	v_mfma_f32_16x16x32_bf16 v[152:155], v[148:151], v[188:191], v[110:113]
	v_mfma_f32_16x16x32_bf16 v[200:203], v[164:167], v[188:191], v[106:109]
	s_setprio 0
	s_barrier
	s_nop 0
	ds_read_b128 v[106:109], v157
	ds_read_b128 v[110:113], v157 offset:1024
	ds_read_b128 v[204:207], v157 offset:2048
	ds_read_b128 v[156:159], v157 offset:3072
	s_barrier
	s_waitcnt lgkmcnt(0)
	s_setprio 1
	v_mfma_f32_16x16x32_bf16 v[86:89], v[106:109], v[176:179], v[86:89]
	v_mfma_f32_16x16x32_bf16 v[82:85], v[204:207], v[176:179], v[82:85]
	v_mfma_f32_16x16x32_bf16 v[70:73], v[106:109], v[192:195], v[70:73]
	v_mfma_f32_16x16x32_bf16 v[66:69], v[204:207], v[192:195], v[66:69]
	v_mfma_f32_16x16x32_bf16 v[94:97], v[106:109], v[168:171], v[94:97]
	v_mfma_f32_16x16x32_bf16 v[90:93], v[204:207], v[168:171], v[90:93]
	v_mfma_f32_16x16x32_bf16 v[86:89], v[110:113], v[180:183], v[86:89]
	v_mfma_f32_16x16x32_bf16 v[82:85], v[156:159], v[180:183], v[82:85]
	v_mfma_f32_16x16x32_bf16 v[78:81], v[106:109], v[184:187], v[78:81]
	v_mfma_f32_16x16x32_bf16 v[74:77], v[204:207], v[184:187], v[74:77]
	v_mfma_f32_16x16x32_bf16 v[70:73], v[110:113], v[196:199], v[70:73]
	v_mfma_f32_16x16x32_bf16 v[66:69], v[156:159], v[196:199], v[66:69]
	v_mfma_f32_16x16x32_bf16 v[236:239], v[110:113], v[172:175], v[94:97]
	v_mfma_f32_16x16x32_bf16 v[168:171], v[156:159], v[172:175], v[90:93]
	v_mfma_f32_16x16x32_bf16 v[172:175], v[110:113], v[188:191], v[78:81]
	v_mfma_f32_16x16x32_bf16 v[176:179], v[156:159], v[188:191], v[74:77]
	s_setprio 0
	s_barrier
; #define WAIT_V(n) asm volatile("s_waitcnt vmcnt(" #n ")" ::: "memory")
; #define WAIT_L(n) asm volatile("s_waitcnt lgkmcnt(" #n ")" ::: "memory")
; #define BAR __builtin_amdgcn_s_barrier()
; template <int MODE>
; __device__ __forceinline__ void gemm_tile(const int ph, const int which, const int pm, const int pn) {
;     ...
;     LDA(At, 0, 1); WAIT_V(4); BAR; WAIT_L(0); MMA(1, 0, At, B0); MMA(1, 1, At, B1); BAR;
;   }
;   {
;     LDB(B0, 1, 0); LDA(At, 1, 0); WAIT_V(2); BAR; WAIT_L(0); MMA(0, 0, At, B0); BAR;
	s_nop 0
	ds_read_b128 v[74:77], v137 offset:16384
	ds_read_b128 v[78:81], v137 offset:17408
	ds_read_b128 v[90:93], v136 offset:16384
	ds_read_b128 v[94:97], v136 offset:17408
	ds_read_b128 v[180:183], v135 offset:16384
	ds_read_b128 v[184:187], v135 offset:17408
	ds_read_b128 v[188:191], v134 offset:16384
	ds_read_b128 v[192:195], v134 offset:17408
	s_waitcnt vmcnt(4)
	s_barrier
	s_waitcnt lgkmcnt(0)
	s_setprio 1
	v_mfma_f32_16x16x32_bf16 v[62:65], v[142:145], v[74:77], v[62:65]
	v_mfma_f32_16x16x32_bf16 v[58:61], v[160:163], v[74:77], v[58:61]
	v_mfma_f32_16x16x32_bf16 v[54:57], v[142:145], v[90:93], v[54:57]
	v_mfma_f32_16x16x32_bf16 v[50:53], v[160:163], v[90:93], v[50:53]
	v_mfma_f32_16x16x32_bf16 v[38:41], v[142:145], v[188:191], v[38:41]
	v_mfma_f32_16x16x32_bf16 v[34:37], v[160:163], v[188:191], v[34:37]
	v_mfma_f32_16x16x32_bf16 v[62:65], v[148:151], v[78:81], v[62:65]
	v_mfma_f32_16x16x32_bf16 v[58:61], v[164:167], v[78:81], v[58:61]
	v_mfma_f32_16x16x32_bf16 v[54:57], v[148:151], v[94:97], v[54:57]
	v_mfma_f32_16x16x32_bf16 v[50:53], v[164:167], v[94:97], v[50:53]
	v_mfma_f32_16x16x32_bf16 v[46:49], v[142:145], v[180:183], v[46:49]
	v_mfma_f32_16x16x32_bf16 v[42:45], v[160:163], v[180:183], v[42:45]
	v_mfma_f32_16x16x32_bf16 v[38:41], v[148:151], v[192:195], v[38:41]
	v_mfma_f32_16x16x32_bf16 v[34:37], v[164:167], v[192:195], v[34:37]
	v_mfma_f32_16x16x32_bf16 v[196:199], v[148:151], v[184:187], v[46:49]
	v_mfma_f32_16x16x32_bf16 v[240:243], v[164:167], v[184:187], v[42:45]
	s_setprio 0
	s_setprio 1
	v_mfma_f32_16x16x32_bf16 v[22:25], v[106:109], v[90:93], v[22:25]
	v_mfma_f32_16x16x32_bf16 v[18:21], v[204:207], v[90:93], v[18:21]
	v_mfma_f32_16x16x32_bf16 v[6:9], v[106:109], v[188:191], v[6:9]
	v_mfma_f32_16x16x32_bf16 v[2:5], v[204:207], v[188:191], v[2:5]
	v_mfma_f32_16x16x32_bf16 v[30:33], v[106:109], v[74:77], v[30:33]
	v_mfma_f32_16x16x32_bf16 v[26:29], v[204:207], v[74:77], v[26:29]
	v_mfma_f32_16x16x32_bf16 v[22:25], v[110:113], v[94:97], v[22:25]
	v_mfma_f32_16x16x32_bf16 v[18:21], v[156:159], v[94:97], v[18:21]
	v_mfma_f32_16x16x32_bf16 v[14:17], v[106:109], v[180:183], v[14:17]
	v_mfma_f32_16x16x32_bf16 v[10:13], v[204:207], v[180:183], v[10:13]
	v_mfma_f32_16x16x32_bf16 v[6:9], v[110:113], v[192:195], v[6:9]
	v_mfma_f32_16x16x32_bf16 v[2:5], v[156:159], v[192:195], v[2:5]
	v_mfma_f32_16x16x32_bf16 v[142:145], v[110:113], v[78:81], v[30:33]
	v_mfma_f32_16x16x32_bf16 v[148:151], v[156:159], v[78:81], v[26:29]
	v_mfma_f32_16x16x32_bf16 v[160:163], v[110:113], v[184:187], v[14:17]
	v_mfma_f32_16x16x32_bf16 v[164:167], v[156:159], v[184:187], v[10:13]
	s_setprio 0
	s_barrier
	s_nop 0
	ds_read_b128 v[10:13], v146
	ds_read_b128 v[14:17], v146 offset:1024
	ds_read_b128 v[156:159], v146 offset:2048
	ds_read_b128 v[180:183], v146 offset:3072
	ds_read_b128 v[26:29], v137 offset:32768
	ds_read_b128 v[30:33], v137 offset:33792
	ds_read_b128 v[42:45], v136 offset:32768
	ds_read_b128 v[46:49], v136 offset:33792
	ds_read_b128 v[184:187], v135 offset:32768
	ds_read_b128 v[188:191], v135 offset:33792
	ds_read_b128 v[192:195], v134 offset:32768
	ds_read_b128 v[204:207], v134 offset:33792
	s_waitcnt vmcnt(2)
	s_barrier
	s_waitcnt lgkmcnt(0)
	s_setprio 1
	v_mfma_f32_16x16x32_bf16 v[74:77], v[10:13], v[26:29], v[126:129]
	v_mfma_f32_16x16x32_bf16 v[126:129], v[14:17], v[30:33], v[74:77]
	v_mfma_f32_16x16x32_bf16 v[74:77], v[156:159], v[26:29], v[122:125]
	v_mfma_f32_16x16x32_bf16 v[122:125], v[180:183], v[30:33], v[74:77]
	v_mfma_f32_16x16x32_bf16 v[74:77], v[10:13], v[42:45], v[118:121]
	v_mfma_f32_16x16x32_bf16 v[110:113], v[14:17], v[46:49], v[74:77]
	v_mfma_f32_16x16x32_bf16 v[74:77], v[156:159], v[42:45], v[114:117]
	v_mfma_f32_16x16x32_bf16 v[106:109], v[180:183], v[46:49], v[74:77]
	v_mfma_f32_16x16x32_bf16 v[74:77], v[10:13], v[184:187], v[152:155]
	v_mfma_f32_16x16x32_bf16 v[94:97], v[14:17], v[188:191], v[74:77]
	v_mfma_f32_16x16x32_bf16 v[74:77], v[156:159], v[184:187], v[200:203]
	v_mfma_f32_16x16x32_bf16 v[90:93], v[180:183], v[188:191], v[74:77]
	v_mfma_f32_16x16x32_bf16 v[74:77], v[10:13], v[192:195], v[102:105]
	v_mfma_f32_16x16x32_bf16 v[78:81], v[14:17], v[204:207], v[74:77]
	v_mfma_f32_16x16x32_bf16 v[74:77], v[156:159], v[192:195], v[98:101]
	v_mfma_f32_16x16x32_bf16 v[74:77], v[180:183], v[204:207], v[74:77]
	s_setprio 0
	s_barrier
; #define WAIT_V(n) asm volatile("s_waitcnt vmcnt(" #n ")" ::: "memory")
; #define WAIT_L(n) asm volatile("s_waitcnt lgkmcnt(" #n ")" ::: "memory")
; #define BAR __builtin_amdgcn_s_barrier()
; template <int MODE>
; __device__ __forceinline__ void gemm_tile(const int ph, const int which, const int pm, const int pn) {
;     ...
;     LDB(B1, 1, 1); WAIT_V(0); BAR; WAIT_L(0); MMA(0, 1, At, B1); BAR;
;     LDA(At, 1, 1); BAR; WAIT_L(0); MMA(1, 0, At, B0); MMA(1, 1, At, B1); BAR;
;   }
;   if (wr == 0) BAR;
	ds_read_b128 v[152:155], v140
	ds_read_b128 v[200:203], v140 offset:1024
	ds_read_b128 v[244:247], v140 offset:2048
	ds_read_b128 v[138:141], v140 offset:3072
	s_waitcnt vmcnt(0)
	s_barrier
	s_waitcnt lgkmcnt(0)
	s_setprio 1
	v_mfma_f32_16x16x32_bf16 v[98:101], v[152:155], v[26:29], v[236:239]
	v_mfma_f32_16x16x32_bf16 v[26:29], v[244:247], v[26:29], v[168:171]
	v_mfma_f32_16x16x32_bf16 v[114:117], v[138:141], v[30:33], v[26:29]
	v_mfma_f32_16x16x32_bf16 v[26:29], v[152:155], v[42:45], v[86:89]
	v_mfma_f32_16x16x32_bf16 v[102:105], v[200:203], v[46:49], v[26:29]
	v_mfma_f32_16x16x32_bf16 v[26:29], v[244:247], v[42:45], v[82:85]
	v_mfma_f32_16x16x32_bf16 v[118:121], v[200:203], v[30:33], v[98:101]
	v_mfma_f32_16x16x32_bf16 v[98:101], v[138:141], v[46:49], v[26:29]
	v_mfma_f32_16x16x32_bf16 v[26:29], v[152:155], v[184:187], v[172:175]
	v_mfma_f32_16x16x32_bf16 v[86:89], v[200:203], v[188:191], v[26:29]
	v_mfma_f32_16x16x32_bf16 v[26:29], v[244:247], v[184:187], v[176:179]
	v_mfma_f32_16x16x32_bf16 v[82:85], v[138:141], v[188:191], v[26:29]
	v_mfma_f32_16x16x32_bf16 v[26:29], v[152:155], v[192:195], v[70:73]
	v_mfma_f32_16x16x32_bf16 v[70:73], v[200:203], v[204:207], v[26:29]
	v_mfma_f32_16x16x32_bf16 v[26:29], v[244:247], v[192:195], v[66:69]
	v_mfma_f32_16x16x32_bf16 v[66:69], v[138:141], v[204:207], v[26:29]
	s_setprio 0
	s_barrier
	ds_read_b128 v[168:171], v137 offset:49152
	ds_read_b128 v[172:175], v137 offset:50176
	ds_read_b128 v[176:179], v136 offset:49152
	ds_read_b128 v[184:187], v136 offset:50176
	ds_read_b128 v[188:191], v135 offset:49152
	ds_read_b128 v[192:195], v135 offset:50176
	ds_read_b128 v[204:207], v134 offset:49152
	ds_read_b128 v[134:137], v134 offset:50176
	s_barrier
	s_waitcnt lgkmcnt(0)
	s_setprio 1
	v_mfma_f32_16x16x32_bf16 v[26:29], v[10:13], v[168:171], v[62:65]
	v_mfma_f32_16x16x32_bf16 v[62:65], v[14:17], v[172:175], v[26:29]
	v_mfma_f32_16x16x32_bf16 v[26:29], v[156:159], v[168:171], v[58:61]
	v_mfma_f32_16x16x32_bf16 v[58:61], v[180:183], v[172:175], v[26:29]
	v_mfma_f32_16x16x32_bf16 v[26:29], v[10:13], v[176:179], v[54:57]
	v_mfma_f32_16x16x32_bf16 v[46:49], v[14:17], v[184:187], v[26:29]
	v_mfma_f32_16x16x32_bf16 v[26:29], v[156:159], v[176:179], v[50:53]
	v_mfma_f32_16x16x32_bf16 v[42:45], v[180:183], v[184:187], v[26:29]
	v_mfma_f32_16x16x32_bf16 v[26:29], v[10:13], v[188:191], v[196:199]
	v_mfma_f32_16x16x32_bf16 v[10:13], v[10:13], v[204:207], v[38:41]
	v_mfma_f32_16x16x32_bf16 v[30:33], v[14:17], v[192:195], v[26:29]
	v_mfma_f32_16x16x32_bf16 v[26:29], v[156:159], v[188:191], v[240:243]
	v_mfma_f32_16x16x32_bf16 v[14:17], v[14:17], v[134:137], v[10:13]
	v_mfma_f32_16x16x32_bf16 v[10:13], v[156:159], v[204:207], v[34:37]
	v_mfma_f32_16x16x32_bf16 v[26:29], v[180:183], v[192:195], v[26:29]
	v_mfma_f32_16x16x32_bf16 v[10:13], v[180:183], v[134:137], v[10:13]
	s_setprio 0
	s_setprio 1
	v_mfma_f32_16x16x32_bf16 v[34:37], v[152:155], v[168:171], v[142:145]
	v_mfma_f32_16x16x32_bf16 v[54:57], v[200:203], v[172:175], v[34:37]
	v_mfma_f32_16x16x32_bf16 v[34:37], v[244:247], v[168:171], v[148:151]
	v_mfma_f32_16x16x32_bf16 v[18:21], v[244:247], v[176:179], v[18:21]
	v_mfma_f32_16x16x32_bf16 v[50:53], v[138:141], v[172:175], v[34:37]
	v_mfma_f32_16x16x32_bf16 v[22:25], v[152:155], v[176:179], v[22:25]
	v_mfma_f32_16x16x32_bf16 v[34:37], v[138:141], v[184:187], v[18:21]
	v_mfma_f32_16x16x32_bf16 v[18:21], v[152:155], v[188:191], v[160:163]
	v_mfma_f32_16x16x32_bf16 v[38:41], v[200:203], v[184:187], v[22:25]
	v_mfma_f32_16x16x32_bf16 v[22:25], v[200:203], v[192:195], v[18:21]
	v_mfma_f32_16x16x32_bf16 v[18:21], v[244:247], v[188:191], v[164:167]
	v_mfma_f32_16x16x32_bf16 v[6:9], v[152:155], v[204:207], v[6:9]
	v_mfma_f32_16x16x32_bf16 v[2:5], v[244:247], v[204:207], v[2:5]
	v_mfma_f32_16x16x32_bf16 v[18:21], v[138:141], v[192:195], v[18:21]
	v_mfma_f32_16x16x32_bf16 v[6:9], v[200:203], v[134:137], v[6:9]
	v_mfma_f32_16x16x32_bf16 v[2:5], v[138:141], v[134:137], v[2:5]
	s_setprio 0
	s_movk_i32 s2, 0x100
	v_cmp_gt_u32_e32 vcc, s2, v0
	s_barrier
	s_and_saveexec_b64 s[2:3], vcc
	s_cbranch_execz .LBB0_134
	s_barrier

; #define WAIT_L(n) asm volatile("s_waitcnt lgkmcnt(" #n ")" ::: "memory")
; #define BAR __builtin_amdgcn_s_barrier()
; #define SCHED __builtin_amdgcn_sched_barrier(0)
; template <int MODE>
; __device__ __forceinline__ void gemm_tile(const int ph, const int which, const int pm, const int pn) {
;     ...
;     LDB(B0, 0, 0); SCHED; LDA(At, 0, 0); STAGE(SA(1, 1), RA, brow + HALF, t + 1);
;     WAIT_L(8); BAR; WAIT_L(0); MMA(0, 0, At, B0); BAR; SCHED;
;     LDB(B1, 0, 1); STAGE(SB(0, 0), RB, bcol, t + 2);
;     BAR; WAIT_L(0); MMA(0, 1, At, B1); BAR;
;     LDA(At, 0, 1); STAGE(SA(0, 0), RA, brow, t + 2);
;     BAR; WAIT_L(0); MMA(1, 0, At, B0); BAR; SCHED;
.LBB0_218:
	ds_read_b128 v[158:161], v156
	ds_read_b128 v[162:165], v156 offset:1024
	ds_read_b128 v[166:169], v156 offset:2048
	ds_read_b128 v[170:173], v156 offset:3072
	s_add_i32 s12, s18, s27
	v_readfirstlane_b32 s29, v153
	s_add_i32 s13, s12, 0x80
	s_mov_b32 m0, s29
	ds_read_b128 v[174:177], v134
	ds_read_b128 v[178:181], v134 offset:1024
	ds_read_b128 v[182:185], v133
	ds_read_b128 v[186:189], v133 offset:1024
	ds_read_b128 v[190:193], v132
	ds_read_b128 v[194:197], v132 offset:1024
	ds_read_b128 v[198:201], v131
	ds_read_b128 v[202:205], v131 offset:1024
	buffer_load_dwordx4 v135, s[4:7], s13 offen lds
	s_add_i32 s13, s17, s27
	v_readfirstlane_b32 s38, v151
	s_add_i32 s29, s13, 0x80
	s_mov_b32 m0, s38
	s_nop 0
	buffer_load_dwordx4 v135, s[4:7], s29 offen lds
	s_waitcnt lgkmcnt(8)
	s_barrier
	s_waitcnt lgkmcnt(0)
	s_setprio 1
	v_mfma_f32_16x16x32_bf16 v[126:129], v[158:161], v[174:177], v[126:129]
	v_mfma_f32_16x16x32_bf16 v[122:125], v[166:169], v[174:177], v[122:125]
	v_mfma_f32_16x16x32_bf16 v[118:121], v[158:161], v[182:185], v[118:121]
	v_mfma_f32_16x16x32_bf16 v[114:117], v[166:169], v[182:185], v[114:117]
	v_mfma_f32_16x16x32_bf16 v[110:113], v[158:161], v[190:193], v[110:113]
	v_mfma_f32_16x16x32_bf16 v[106:109], v[166:169], v[190:193], v[106:109]
	v_mfma_f32_16x16x32_bf16 v[102:105], v[158:161], v[198:201], v[102:105]
	v_mfma_f32_16x16x32_bf16 v[98:101], v[166:169], v[198:201], v[98:101]
	v_mfma_f32_16x16x32_bf16 v[126:129], v[162:165], v[178:181], v[126:129]
	v_mfma_f32_16x16x32_bf16 v[122:125], v[170:173], v[178:181], v[122:125]
	v_mfma_f32_16x16x32_bf16 v[118:121], v[162:165], v[186:189], v[118:121]
	v_mfma_f32_16x16x32_bf16 v[114:117], v[170:173], v[186:189], v[114:117]
	v_mfma_f32_16x16x32_bf16 v[110:113], v[162:165], v[194:197], v[110:113]
	v_mfma_f32_16x16x32_bf16 v[106:109], v[170:173], v[194:197], v[106:109]
	v_mfma_f32_16x16x32_bf16 v[102:105], v[162:165], v[202:205], v[102:105]
	v_mfma_f32_16x16x32_bf16 v[98:101], v[170:173], v[202:205], v[98:101]
	s_setprio 0
	s_barrier
	s_add_i32 s29, s26, s27
	v_readfirstlane_b32 s43, v139
	s_add_i32 s38, s29, 0x100
	s_mov_b32 m0, s43
	ds_read_b128 v[236:239], v155
	ds_read_b128 v[240:243], v155 offset:1024
	ds_read_b128 v[244:247], v155 offset:2048
	ds_read_b128 v[248:251], v155 offset:3072
	buffer_load_dwordx4 v135, s[68:71], s38 offen lds
	s_add_i32 s38, s25, s27
	v_readfirstlane_b32 s50, v140
	s_add_i32 s43, s38, 0x100
	s_mov_b32 m0, s50
	s_add_i32 vcc_lo, vcc_lo, 2
	buffer_load_dwordx4 v135, s[68:71], s43 offen lds
	s_barrier
	s_waitcnt lgkmcnt(0)
	s_setprio 1
	v_mfma_f32_16x16x32_bf16 v[94:97], v[236:239], v[174:177], v[94:97]
	v_mfma_f32_16x16x32_bf16 v[90:93], v[244:247], v[174:177], v[90:93]
	v_mfma_f32_16x16x32_bf16 v[86:89], v[236:239], v[182:185], v[86:89]
	v_mfma_f32_16x16x32_bf16 v[82:85], v[244:247], v[182:185], v[82:85]
	v_mfma_f32_16x16x32_bf16 v[78:81], v[236:239], v[190:193], v[78:81]
	v_mfma_f32_16x16x32_bf16 v[74:77], v[244:247], v[190:193], v[74:77]
	v_mfma_f32_16x16x32_bf16 v[70:73], v[236:239], v[198:201], v[70:73]
	v_mfma_f32_16x16x32_bf16 v[66:69], v[244:247], v[198:201], v[66:69]
	v_mfma_f32_16x16x32_bf16 v[94:97], v[240:243], v[178:181], v[94:97]
	v_mfma_f32_16x16x32_bf16 v[90:93], v[248:251], v[178:181], v[90:93]
	v_mfma_f32_16x16x32_bf16 v[86:89], v[240:243], v[186:189], v[86:89]
	v_mfma_f32_16x16x32_bf16 v[82:85], v[248:251], v[186:189], v[82:85]
	v_mfma_f32_16x16x32_bf16 v[78:81], v[240:243], v[194:197], v[78:81]
	v_mfma_f32_16x16x32_bf16 v[74:77], v[248:251], v[194:197], v[74:77]
	v_mfma_f32_16x16x32_bf16 v[70:73], v[240:243], v[202:205], v[70:73]
	v_mfma_f32_16x16x32_bf16 v[66:69], v[248:251], v[202:205], v[66:69]
	s_setprio 0
	s_add_i32 s43, s22, s27
	v_readfirstlane_b32 s51, v136
	s_add_i32 s50, s43, 0x100
	s_mov_b32 m0, s51
	s_barrier
	ds_read_b128 v[174:177], v134 offset:16384
	ds_read_b128 v[178:181], v134 offset:17408
	ds_read_b128 v[182:185], v133 offset:16384
	ds_read_b128 v[186:189], v133 offset:17408
	ds_read_b128 v[190:193], v132 offset:16384
	ds_read_b128 v[194:197], v132 offset:17408
	ds_read_b128 v[198:201], v131 offset:16384
	ds_read_b128 v[202:205], v131 offset:17408
	buffer_load_dwordx4 v135, s[4:7], s50 offen lds
	s_add_i32 s50, s21, s27
	v_readfirstlane_b32 s72, v141
	s_add_i32 s51, s50, 0x100
	s_mov_b32 m0, s72
	s_nop 0
	buffer_load_dwordx4 v135, s[4:7], s51 offen lds
	s_barrier
	s_waitcnt lgkmcnt(0)
	s_setprio 1
	v_mfma_f32_16x16x32_bf16 v[62:65], v[158:161], v[174:177], v[62:65]
	v_mfma_f32_16x16x32_bf16 v[58:61], v[166:169], v[174:177], v[58:61]
	v_mfma_f32_16x16x32_bf16 v[54:57], v[158:161], v[182:185], v[54:57]
	v_mfma_f32_16x16x32_bf16 v[50:53], v[166:169], v[182:185], v[50:53]
	v_mfma_f32_16x16x32_bf16 v[46:49], v[158:161], v[190:193], v[46:49]
	v_mfma_f32_16x16x32_bf16 v[42:45], v[166:169], v[190:193], v[42:45]
	v_mfma_f32_16x16x32_bf16 v[38:41], v[158:161], v[198:201], v[38:41]
	v_mfma_f32_16x16x32_bf16 v[34:37], v[166:169], v[198:201], v[34:37]
	v_mfma_f32_16x16x32_bf16 v[62:65], v[162:165], v[178:181], v[62:65]
	v_mfma_f32_16x16x32_bf16 v[58:61], v[170:173], v[178:181], v[58:61]
	v_mfma_f32_16x16x32_bf16 v[54:57], v[162:165], v[186:189], v[54:57]
	v_mfma_f32_16x16x32_bf16 v[50:53], v[170:173], v[186:189], v[50:53]
	v_mfma_f32_16x16x32_bf16 v[46:49], v[162:165], v[194:197], v[46:49]
	v_mfma_f32_16x16x32_bf16 v[42:45], v[170:173], v[194:197], v[42:45]
	v_mfma_f32_16x16x32_bf16 v[38:41], v[162:165], v[202:205], v[38:41]
	v_mfma_f32_16x16x32_bf16 v[34:37], v[170:173], v[202:205], v[34:37]
	s_setprio 0
	s_barrier
; #define WAIT_V(n) asm volatile("s_waitcnt vmcnt(" #n ")" ::: "memory")
; #define WAIT_L(n) asm volatile("s_waitcnt lgkmcnt(" #n ")" ::: "memory")
; #define BAR __builtin_amdgcn_s_barrier()
; #define SCHED __builtin_amdgcn_sched_barrier(0)
; template <int MODE>
; __device__ __forceinline__ void gemm_tile(const int ph, const int which, const int pm, const int pn) {
;     ...
;     STAGE(SB(0, 1), RB, bcolB, t + 2);
;     WAIT_V(6); BAR; MMA(1, 1, At, B1); BAR;
;     LDB(B0, 1, 0); SCHED; LDA(At, 1, 0); STAGE(SA(0, 1), RA, brow + HALF, t + 2);
;     WAIT_L(8); BAR; WAIT_L(0); MMA(0, 0, At, B0); BAR; SCHED;
;     LDB(B1, 1, 1); STAGE(SB(1, 0), RB, bcol, t + 3);
;     BAR; WAIT_L(0); MMA(0, 1, At, B1); BAR;
;     LDA(At, 1, 1); STAGE(SA(1, 0), RA, brow, t + 3);
	s_add_i32 s51, s20, s27
	v_readfirstlane_b32 s73, v142
	s_add_i32 s72, s51, 0x100
	s_mov_b32 m0, s73
	v_readfirstlane_b32 s86, v143
	buffer_load_dwordx4 v135, s[68:71], s72 offen lds
	s_add_i32 s72, s19, s27
	s_add_i32 s73, s72, 0x100
	s_mov_b32 m0, s86
	s_nop 0
	buffer_load_dwordx4 v135, s[68:71], s73 offen lds
	s_waitcnt vmcnt(6)
	s_barrier
	s_setprio 1
	v_mfma_f32_16x16x32_bf16 v[30:33], v[236:239], v[174:177], v[30:33]
	v_mfma_f32_16x16x32_bf16 v[26:29], v[244:247], v[174:177], v[26:29]
	v_mfma_f32_16x16x32_bf16 v[22:25], v[236:239], v[182:185], v[22:25]
	v_mfma_f32_16x16x32_bf16 v[18:21], v[244:247], v[182:185], v[18:21]
	v_mfma_f32_16x16x32_bf16 v[14:17], v[236:239], v[190:193], v[14:17]
	v_mfma_f32_16x16x32_bf16 v[10:13], v[244:247], v[190:193], v[10:13]
	v_mfma_f32_16x16x32_bf16 v[6:9], v[236:239], v[198:201], v[6:9]
	v_mfma_f32_16x16x32_bf16 v[2:5], v[244:247], v[198:201], v[2:5]
	v_mfma_f32_16x16x32_bf16 v[30:33], v[240:243], v[178:181], v[30:33]
	v_mfma_f32_16x16x32_bf16 v[26:29], v[248:251], v[178:181], v[26:29]
	v_mfma_f32_16x16x32_bf16 v[22:25], v[240:243], v[186:189], v[22:25]
	v_mfma_f32_16x16x32_bf16 v[18:21], v[248:251], v[186:189], v[18:21]
	v_mfma_f32_16x16x32_bf16 v[14:17], v[240:243], v[194:197], v[14:17]
	v_mfma_f32_16x16x32_bf16 v[10:13], v[248:251], v[194:197], v[10:13]
	v_mfma_f32_16x16x32_bf16 v[6:9], v[240:243], v[202:205], v[6:9]
	v_mfma_f32_16x16x32_bf16 v[2:5], v[248:251], v[202:205], v[2:5]
	s_setprio 0
	s_barrier
	ds_read_b128 v[158:161], v144
	ds_read_b128 v[162:165], v144 offset:1024
	ds_read_b128 v[166:169], v144 offset:2048
	ds_read_b128 v[170:173], v144 offset:3072
	v_readfirstlane_b32 s73, v145
	s_addk_i32 s12, 0x100
	s_mov_b32 m0, s73
	ds_read_b128 v[174:177], v134 offset:32768
	ds_read_b128 v[178:181], v134 offset:33792
	ds_read_b128 v[182:185], v133 offset:32768
	ds_read_b128 v[186:189], v133 offset:33792
	ds_read_b128 v[190:193], v132 offset:32768
	ds_read_b128 v[194:197], v132 offset:33792
	ds_read_b128 v[198:201], v131 offset:32768
	ds_read_b128 v[202:205], v131 offset:33792
	buffer_load_dwordx4 v135, s[4:7], s12 offen lds
	v_readfirstlane_b32 s12, v146
	s_addk_i32 s13, 0x100
	s_mov_b32 m0, s12
	s_nop 0
	buffer_load_dwordx4 v135, s[4:7], s13 offen lds
	s_waitcnt lgkmcnt(8)
	s_barrier
	s_waitcnt lgkmcnt(0)
	s_setprio 1
	v_mfma_f32_16x16x32_bf16 v[126:129], v[158:161], v[174:177], v[126:129]
	v_mfma_f32_16x16x32_bf16 v[122:125], v[166:169], v[174:177], v[122:125]
	v_mfma_f32_16x16x32_bf16 v[118:121], v[158:161], v[182:185], v[118:121]
	v_mfma_f32_16x16x32_bf16 v[114:117], v[166:169], v[182:185], v[114:117]
	v_mfma_f32_16x16x32_bf16 v[110:113], v[158:161], v[190:193], v[110:113]
	v_mfma_f32_16x16x32_bf16 v[106:109], v[166:169], v[190:193], v[106:109]
	v_mfma_f32_16x16x32_bf16 v[102:105], v[158:161], v[198:201], v[102:105]
	v_mfma_f32_16x16x32_bf16 v[98:101], v[166:169], v[198:201], v[98:101]
	v_mfma_f32_16x16x32_bf16 v[126:129], v[162:165], v[178:181], v[126:129]
	v_mfma_f32_16x16x32_bf16 v[122:125], v[170:173], v[178:181], v[122:125]
	v_mfma_f32_16x16x32_bf16 v[118:121], v[162:165], v[186:189], v[118:121]
	v_mfma_f32_16x16x32_bf16 v[114:117], v[170:173], v[186:189], v[114:117]
	v_mfma_f32_16x16x32_bf16 v[110:113], v[162:165], v[194:197], v[110:113]
	v_mfma_f32_16x16x32_bf16 v[106:109], v[170:173], v[194:197], v[106:109]
	v_mfma_f32_16x16x32_bf16 v[102:105], v[162:165], v[202:205], v[102:105]
	v_mfma_f32_16x16x32_bf16 v[98:101], v[170:173], v[202:205], v[98:101]
	s_setprio 0
	s_barrier
	v_readfirstlane_b32 s12, v147
	s_addk_i32 s29, 0x180
	s_mov_b32 m0, s12
	v_readfirstlane_b32 s12, v148
	ds_read_b128 v[236:239], v137
	ds_read_b128 v[240:243], v137 offset:1024
	ds_read_b128 v[244:247], v137 offset:2048
	ds_read_b128 v[248:251], v137 offset:3072
	buffer_load_dwordx4 v135, s[68:71], s29 offen lds
	s_addk_i32 s38, 0x180
	s_mov_b32 m0, s12
	s_nop 0
	buffer_load_dwordx4 v135, s[68:71], s38 offen lds
	s_barrier
	s_waitcnt lgkmcnt(0)
	s_setprio 1
	v_mfma_f32_16x16x32_bf16 v[94:97], v[236:239], v[174:177], v[94:97]
	v_mfma_f32_16x16x32_bf16 v[90:93], v[244:247], v[174:177], v[90:93]
	v_mfma_f32_16x16x32_bf16 v[86:89], v[236:239], v[182:185], v[86:89]
	v_mfma_f32_16x16x32_bf16 v[82:85], v[244:247], v[182:185], v[82:85]
	v_mfma_f32_16x16x32_bf16 v[78:81], v[236:239], v[190:193], v[78:81]
	v_mfma_f32_16x16x32_bf16 v[74:77], v[244:247], v[190:193], v[74:77]
	v_mfma_f32_16x16x32_bf16 v[70:73], v[236:239], v[198:201], v[70:73]
	v_mfma_f32_16x16x32_bf16 v[66:69], v[244:247], v[198:201], v[66:69]
	v_mfma_f32_16x16x32_bf16 v[94:97], v[240:243], v[178:181], v[94:97]
	v_mfma_f32_16x16x32_bf16 v[90:93], v[248:251], v[178:181], v[90:93]
	v_mfma_f32_16x16x32_bf16 v[86:89], v[240:243], v[186:189], v[86:89]
	v_mfma_f32_16x16x32_bf16 v[82:85], v[248:251], v[186:189], v[82:85]
	v_mfma_f32_16x16x32_bf16 v[78:81], v[240:243], v[194:197], v[78:81]
	v_mfma_f32_16x16x32_bf16 v[74:77], v[248:251], v[194:197], v[74:77]
	v_mfma_f32_16x16x32_bf16 v[70:73], v[240:243], v[202:205], v[70:73]
	v_mfma_f32_16x16x32_bf16 v[66:69], v[248:251], v[202:205], v[66:69]
	s_setprio 0
	v_readfirstlane_b32 s12, v149
	s_addk_i32 s43, 0x180
	s_mov_b32 m0, s12
	v_readfirstlane_b32 s12, v150
	s_barrier
	ds_read_b128 v[174:177], v134 offset:49152
	ds_read_b128 v[178:181], v134 offset:50176
	ds_read_b128 v[182:185], v133 offset:49152
	ds_read_b128 v[186:189], v133 offset:50176
	ds_read_b128 v[190:193], v132 offset:49152
	ds_read_b128 v[194:197], v132 offset:50176
	ds_read_b128 v[198:201], v131 offset:49152
	ds_read_b128 v[202:205], v131 offset:50176
	buffer_load_dwordx4 v135, s[4:7], s43 offen lds
	s_addk_i32 s50, 0x180
	s_mov_b32 m0, s12
	s_nop 0
	buffer_load_dwordx4 v135, s[4:7], s50 offen lds
	s_barrier
; #define WAIT_V(n) asm volatile("s_waitcnt vmcnt(" #n ")" ::: "memory")
; #define WAIT_L(n) asm volatile("s_waitcnt lgkmcnt(" #n ")" ::: "memory")
; #define BAR __builtin_amdgcn_s_barrier()
; #define SCHED __builtin_amdgcn_sched_barrier(0)
; template <int MODE>
; __device__ __forceinline__ void gemm_tile(const int ph, const int which, const int pm, const int pn) {
;     ...
;     BAR; WAIT_L(0); MMA(1, 0, At, B0); BAR; SCHED;
;     STAGE(SB(1, 1), RB, bcolB, t + 3);
;     WAIT_V(6); BAR; MMA(1, 1, At, B1); BAR;
;   }
;   {
;     LDB(B0, 0, 0); LDA(At, 0, 0); STAGE(SA(1, 1), RA, brow + HALF, nt - 1);
;     BAR; WAIT_L(0); MMA(0, 0, At, B0); BAR;
;     LDB(B1, 0, 1); BAR; WAIT_L(0); MMA(0, 1, At, B1); BAR;
	s_waitcnt lgkmcnt(0)
	s_setprio 1
	v_mfma_f32_16x16x32_bf16 v[62:65], v[158:161], v[174:177], v[62:65]
	v_mfma_f32_16x16x32_bf16 v[58:61], v[166:169], v[174:177], v[58:61]
	v_mfma_f32_16x16x32_bf16 v[54:57], v[158:161], v[182:185], v[54:57]
	v_mfma_f32_16x16x32_bf16 v[50:53], v[166:169], v[182:185], v[50:53]
	v_mfma_f32_16x16x32_bf16 v[46:49], v[158:161], v[190:193], v[46:49]
	v_mfma_f32_16x16x32_bf16 v[42:45], v[166:169], v[190:193], v[42:45]
	v_mfma_f32_16x16x32_bf16 v[38:41], v[158:161], v[198:201], v[38:41]
	v_mfma_f32_16x16x32_bf16 v[34:37], v[166:169], v[198:201], v[34:37]
	v_mfma_f32_16x16x32_bf16 v[62:65], v[162:165], v[178:181], v[62:65]
	v_mfma_f32_16x16x32_bf16 v[58:61], v[170:173], v[178:181], v[58:61]
	v_mfma_f32_16x16x32_bf16 v[54:57], v[162:165], v[186:189], v[54:57]
	v_mfma_f32_16x16x32_bf16 v[50:53], v[170:173], v[186:189], v[50:53]
	v_mfma_f32_16x16x32_bf16 v[46:49], v[162:165], v[194:197], v[46:49]
	v_mfma_f32_16x16x32_bf16 v[42:45], v[170:173], v[194:197], v[42:45]
	v_mfma_f32_16x16x32_bf16 v[38:41], v[162:165], v[202:205], v[38:41]
	v_mfma_f32_16x16x32_bf16 v[34:37], v[170:173], v[202:205], v[34:37]
	s_setprio 0
	s_barrier
	v_readfirstlane_b32 s12, v152
	s_addk_i32 s51, 0x180
	s_mov_b32 m0, s12
	v_readfirstlane_b32 s12, v154
	buffer_load_dwordx4 v135, s[68:71], s51 offen lds
	s_addk_i32 s72, 0x180
	s_mov_b32 m0, s12
	s_nop 0
	buffer_load_dwordx4 v135, s[68:71], s72 offen lds
	s_waitcnt vmcnt(6)
	s_barrier
	s_setprio 1
	v_mfma_f32_16x16x32_bf16 v[30:33], v[236:239], v[174:177], v[30:33]
	v_mfma_f32_16x16x32_bf16 v[26:29], v[244:247], v[174:177], v[26:29]
	v_mfma_f32_16x16x32_bf16 v[22:25], v[236:239], v[182:185], v[22:25]
	v_mfma_f32_16x16x32_bf16 v[18:21], v[244:247], v[182:185], v[18:21]
	v_mfma_f32_16x16x32_bf16 v[14:17], v[236:239], v[190:193], v[14:17]
	v_mfma_f32_16x16x32_bf16 v[10:13], v[244:247], v[190:193], v[10:13]
	v_mfma_f32_16x16x32_bf16 v[6:9], v[236:239], v[198:201], v[6:9]
	v_mfma_f32_16x16x32_bf16 v[2:5], v[244:247], v[198:201], v[2:5]
	v_mfma_f32_16x16x32_bf16 v[30:33], v[240:243], v[178:181], v[30:33]
	v_mfma_f32_16x16x32_bf16 v[26:29], v[248:251], v[178:181], v[26:29]
	v_mfma_f32_16x16x32_bf16 v[22:25], v[240:243], v[186:189], v[22:25]
	v_mfma_f32_16x16x32_bf16 v[18:21], v[248:251], v[186:189], v[18:21]
	v_mfma_f32_16x16x32_bf16 v[14:17], v[240:243], v[194:197], v[14:17]
	v_mfma_f32_16x16x32_bf16 v[10:13], v[248:251], v[194:197], v[10:13]
	v_mfma_f32_16x16x32_bf16 v[6:9], v[240:243], v[202:205], v[6:9]
	v_mfma_f32_16x16x32_bf16 v[2:5], v[248:251], v[202:205], v[2:5]
	s_setprio 0
	s_addk_i32 s27, 0x100
	s_cmp_lt_u32 vcc_lo, s16
	s_barrier
	s_cbranch_scc1 .LBB0_218
	s_add_i32 s6, s28, s11
	s_lshl_b32 s6, s6, 1
	v_readfirstlane_b32 s12, v153
	s_add_i32 s11, s6, 0xffffff80
	s_mov_b32 s6, s70
	s_mov_b32 s7, s71
	s_mov_b32 m0, s12
	ds_read_b128 v[140:143], v156
	ds_read_b128 v[146:149], v156 offset:1024
	ds_read_b128 v[158:161], v156 offset:2048
	ds_read_b128 v[162:165], v156 offset:3072
	ds_read_b128 v[166:169], v134
	ds_read_b128 v[170:173], v134 offset:1024
	ds_read_b128 v[174:177], v133
	ds_read_b128 v[178:181], v133 offset:1024
	ds_read_b128 v[182:185], v132
	ds_read_b128 v[186:189], v132 offset:1024
	ds_read_b128 v[190:193], v131
	ds_read_b128 v[194:197], v131 offset:1024
	buffer_load_dwordx4 v135, s[4:7], s11 offen lds
	s_add_i32 s11, s11, s10
	v_readfirstlane_b32 s10, v151
	s_mov_b32 m0, s10
	s_nop 0
	buffer_load_dwordx4 v135, s[4:7], s11 offen lds
	s_barrier
	s_waitcnt lgkmcnt(0)
	s_setprio 1
	v_mfma_f32_16x16x32_bf16 v[126:129], v[140:143], v[166:169], v[126:129]
	v_mfma_f32_16x16x32_bf16 v[122:125], v[158:161], v[166:169], v[122:125]
	v_mfma_f32_16x16x32_bf16 v[118:121], v[140:143], v[174:177], v[118:121]
	v_mfma_f32_16x16x32_bf16 v[114:117], v[158:161], v[174:177], v[114:117]
	v_mfma_f32_16x16x32_bf16 v[102:105], v[140:143], v[190:193], v[102:105]
	v_mfma_f32_16x16x32_bf16 v[98:101], v[158:161], v[190:193], v[98:101]
	v_mfma_f32_16x16x32_bf16 v[126:129], v[146:149], v[170:173], v[126:129]
	v_mfma_f32_16x16x32_bf16 v[122:125], v[162:165], v[170:173], v[122:125]
	v_mfma_f32_16x16x32_bf16 v[118:121], v[146:149], v[178:181], v[118:121]
	v_mfma_f32_16x16x32_bf16 v[114:117], v[162:165], v[178:181], v[114:117]
	v_mfma_f32_16x16x32_bf16 v[110:113], v[140:143], v[182:185], v[110:113]
	v_mfma_f32_16x16x32_bf16 v[106:109], v[158:161], v[182:185], v[106:109]
	v_mfma_f32_16x16x32_bf16 v[102:105], v[146:149], v[194:197], v[102:105]
	v_mfma_f32_16x16x32_bf16 v[98:101], v[162:165], v[194:197], v[98:101]
	v_mfma_f32_16x16x32_bf16 v[150:153], v[146:149], v[186:189], v[110:113]
	v_mfma_f32_16x16x32_bf16 v[198:201], v[162:165], v[186:189], v[106:109]
	s_setprio 0
	s_barrier
	s_nop 0
	ds_read_b128 v[106:109], v155
	ds_read_b128 v[110:113], v155 offset:1024
	ds_read_b128 v[202:205], v155 offset:2048
	ds_read_b128 v[154:157], v155 offset:3072
	s_barrier
	s_waitcnt lgkmcnt(0)
	s_setprio 1
	v_mfma_f32_16x16x32_bf16 v[86:89], v[106:109], v[174:177], v[86:89]
	v_mfma_f32_16x16x32_bf16 v[82:85], v[202:205], v[174:177], v[82:85]
	v_mfma_f32_16x16x32_bf16 v[70:73], v[106:109], v[190:193], v[70:73]
	v_mfma_f32_16x16x32_bf16 v[66:69], v[202:205], v[190:193], v[66:69]
	v_mfma_f32_16x16x32_bf16 v[94:97], v[106:109], v[166:169], v[94:97]
	v_mfma_f32_16x16x32_bf16 v[90:93], v[202:205], v[166:169], v[90:93]
	v_mfma_f32_16x16x32_bf16 v[86:89], v[110:113], v[178:181], v[86:89]
	v_mfma_f32_16x16x32_bf16 v[82:85], v[154:157], v[178:181], v[82:85]
	v_mfma_f32_16x16x32_bf16 v[78:81], v[106:109], v[182:185], v[78:81]
	v_mfma_f32_16x16x32_bf16 v[74:77], v[202:205], v[182:185], v[74:77]
	v_mfma_f32_16x16x32_bf16 v[70:73], v[110:113], v[194:197], v[70:73]
	v_mfma_f32_16x16x32_bf16 v[66:69], v[154:157], v[194:197], v[66:69]
	v_mfma_f32_16x16x32_bf16 v[236:239], v[110:113], v[170:173], v[94:97]
	v_mfma_f32_16x16x32_bf16 v[166:169], v[154:157], v[170:173], v[90:93]
	v_mfma_f32_16x16x32_bf16 v[170:173], v[110:113], v[186:189], v[78:81]
	v_mfma_f32_16x16x32_bf16 v[174:177], v[154:157], v[186:189], v[74:77]
	s_setprio 0
	s_barrier
; #define WAIT_V(n) asm volatile("s_waitcnt vmcnt(" #n ")" ::: "memory")
; #define WAIT_L(n) asm volatile("s_waitcnt lgkmcnt(" #n ")" ::: "memory")
; #define BAR __builtin_amdgcn_s_barrier()
; template <int MODE>
; __device__ __forceinline__ void gemm_tile(const int ph, const int which, const int pm, const int pn) {
;     ...
;     LDA(At, 0, 1); WAIT_V(4); BAR; WAIT_L(0); MMA(1, 0, At, B0); MMA(1, 1, At, B1); BAR;
;   }
;   {
;     LDB(B0, 1, 0); LDA(At, 1, 0); WAIT_V(2); BAR; WAIT_L(0); MMA(0, 0, At, B0); BAR;
	s_nop 0
	ds_read_b128 v[74:77], v134 offset:16384
	ds_read_b128 v[78:81], v134 offset:17408
	ds_read_b128 v[90:93], v133 offset:16384
	ds_read_b128 v[94:97], v133 offset:17408
	ds_read_b128 v[178:181], v132 offset:16384
	ds_read_b128 v[182:185], v132 offset:17408
	ds_read_b128 v[186:189], v131 offset:16384
	ds_read_b128 v[190:193], v131 offset:17408
	s_waitcnt vmcnt(4)
	s_barrier
	s_waitcnt lgkmcnt(0)
	s_setprio 1
	v_mfma_f32_16x16x32_bf16 v[62:65], v[140:143], v[74:77], v[62:65]
	v_mfma_f32_16x16x32_bf16 v[58:61], v[158:161], v[74:77], v[58:61]
	v_mfma_f32_16x16x32_bf16 v[54:57], v[140:143], v[90:93], v[54:57]
	v_mfma_f32_16x16x32_bf16 v[50:53], v[158:161], v[90:93], v[50:53]
	v_mfma_f32_16x16x32_bf16 v[38:41], v[140:143], v[186:189], v[38:41]
	v_mfma_f32_16x16x32_bf16 v[34:37], v[158:161], v[186:189], v[34:37]
	v_mfma_f32_16x16x32_bf16 v[62:65], v[146:149], v[78:81], v[62:65]
	v_mfma_f32_16x16x32_bf16 v[58:61], v[162:165], v[78:81], v[58:61]
	v_mfma_f32_16x16x32_bf16 v[54:57], v[146:149], v[94:97], v[54:57]
	v_mfma_f32_16x16x32_bf16 v[50:53], v[162:165], v[94:97], v[50:53]
	v_mfma_f32_16x16x32_bf16 v[46:49], v[140:143], v[178:181], v[46:49]
	v_mfma_f32_16x16x32_bf16 v[42:45], v[158:161], v[178:181], v[42:45]
	v_mfma_f32_16x16x32_bf16 v[38:41], v[146:149], v[190:193], v[38:41]
	v_mfma_f32_16x16x32_bf16 v[34:37], v[162:165], v[190:193], v[34:37]
	v_mfma_f32_16x16x32_bf16 v[194:197], v[146:149], v[182:185], v[46:49]
	v_mfma_f32_16x16x32_bf16 v[240:243], v[162:165], v[182:185], v[42:45]
	s_setprio 0
	s_setprio 1
	v_mfma_f32_16x16x32_bf16 v[22:25], v[106:109], v[90:93], v[22:25]
	v_mfma_f32_16x16x32_bf16 v[18:21], v[202:205], v[90:93], v[18:21]
	v_mfma_f32_16x16x32_bf16 v[6:9], v[106:109], v[186:189], v[6:9]
	v_mfma_f32_16x16x32_bf16 v[2:5], v[202:205], v[186:189], v[2:5]
	v_mfma_f32_16x16x32_bf16 v[30:33], v[106:109], v[74:77], v[30:33]
	v_mfma_f32_16x16x32_bf16 v[26:29], v[202:205], v[74:77], v[26:29]
	v_mfma_f32_16x16x32_bf16 v[22:25], v[110:113], v[94:97], v[22:25]
	v_mfma_f32_16x16x32_bf16 v[18:21], v[154:157], v[94:97], v[18:21]
	v_mfma_f32_16x16x32_bf16 v[14:17], v[106:109], v[178:181], v[14:17]
	v_mfma_f32_16x16x32_bf16 v[10:13], v[202:205], v[178:181], v[10:13]
	v_mfma_f32_16x16x32_bf16 v[6:9], v[110:113], v[190:193], v[6:9]
	v_mfma_f32_16x16x32_bf16 v[2:5], v[154:157], v[190:193], v[2:5]
	v_mfma_f32_16x16x32_bf16 v[140:143], v[110:113], v[78:81], v[30:33]
	v_mfma_f32_16x16x32_bf16 v[146:149], v[154:157], v[78:81], v[26:29]
	v_mfma_f32_16x16x32_bf16 v[158:161], v[110:113], v[182:185], v[14:17]
	v_mfma_f32_16x16x32_bf16 v[162:165], v[154:157], v[182:185], v[10:13]
	s_setprio 0
	s_barrier
	s_nop 0
	ds_read_b128 v[10:13], v144
	ds_read_b128 v[14:17], v144 offset:1024
	ds_read_b128 v[154:157], v144 offset:2048
	ds_read_b128 v[178:181], v144 offset:3072
	ds_read_b128 v[26:29], v134 offset:32768
	ds_read_b128 v[30:33], v134 offset:33792
	ds_read_b128 v[42:45], v133 offset:32768
	ds_read_b128 v[46:49], v133 offset:33792
	ds_read_b128 v[182:185], v132 offset:32768
	ds_read_b128 v[186:189], v132 offset:33792
	ds_read_b128 v[190:193], v131 offset:32768
	ds_read_b128 v[202:205], v131 offset:33792
	s_waitcnt vmcnt(2)
	s_barrier
	s_waitcnt lgkmcnt(0)
	s_setprio 1
	v_mfma_f32_16x16x32_bf16 v[74:77], v[10:13], v[26:29], v[126:129]
	v_mfma_f32_16x16x32_bf16 v[126:129], v[14:17], v[30:33], v[74:77]
	v_mfma_f32_16x16x32_bf16 v[74:77], v[154:157], v[26:29], v[122:125]
	v_mfma_f32_16x16x32_bf16 v[122:125], v[178:181], v[30:33], v[74:77]
	v_mfma_f32_16x16x32_bf16 v[74:77], v[10:13], v[42:45], v[118:121]
	v_mfma_f32_16x16x32_bf16 v[110:113], v[14:17], v[46:49], v[74:77]
	v_mfma_f32_16x16x32_bf16 v[74:77], v[154:157], v[42:45], v[114:117]
	v_mfma_f32_16x16x32_bf16 v[106:109], v[178:181], v[46:49], v[74:77]
	v_mfma_f32_16x16x32_bf16 v[74:77], v[10:13], v[182:185], v[150:153]
	v_mfma_f32_16x16x32_bf16 v[94:97], v[14:17], v[186:189], v[74:77]
	v_mfma_f32_16x16x32_bf16 v[74:77], v[154:157], v[182:185], v[198:201]
	v_mfma_f32_16x16x32_bf16 v[90:93], v[178:181], v[186:189], v[74:77]
	v_mfma_f32_16x16x32_bf16 v[74:77], v[10:13], v[190:193], v[102:105]
	v_mfma_f32_16x16x32_bf16 v[78:81], v[14:17], v[202:205], v[74:77]
	v_mfma_f32_16x16x32_bf16 v[74:77], v[154:157], v[190:193], v[98:101]
	v_mfma_f32_16x16x32_bf16 v[74:77], v[178:181], v[202:205], v[74:77]
	s_setprio 0
	s_barrier
; #define WAIT_V(n) asm volatile("s_waitcnt vmcnt(" #n ")" ::: "memory")
; #define WAIT_L(n) asm volatile("s_waitcnt lgkmcnt(" #n ")" ::: "memory")
; #define BAR __builtin_amdgcn_s_barrier()
; template <int MODE>
; __device__ __forceinline__ void gemm_tile(const int ph, const int which, const int pm, const int pn) {
;     ...
;     LDB(B1, 1, 1); WAIT_V(0); BAR; WAIT_L(0); MMA(0, 1, At, B1); BAR;
;     LDA(At, 1, 1); BAR; WAIT_L(0); MMA(1, 0, At, B0); MMA(1, 1, At, B1); BAR;
;   }
;   if (wr == 0) BAR;
	ds_read_b128 v[150:153], v137
	ds_read_b128 v[198:201], v137 offset:1024
	ds_read_b128 v[244:247], v137 offset:2048
	ds_read_b128 v[248:251], v137 offset:3072
	s_waitcnt vmcnt(0)
	s_barrier
	s_waitcnt lgkmcnt(0)
	s_setprio 1
	v_mfma_f32_16x16x32_bf16 v[98:101], v[150:153], v[26:29], v[236:239]
	v_mfma_f32_16x16x32_bf16 v[26:29], v[244:247], v[26:29], v[166:169]
	v_mfma_f32_16x16x32_bf16 v[114:117], v[248:251], v[30:33], v[26:29]
	v_mfma_f32_16x16x32_bf16 v[26:29], v[150:153], v[42:45], v[86:89]
	v_mfma_f32_16x16x32_bf16 v[102:105], v[198:201], v[46:49], v[26:29]
	v_mfma_f32_16x16x32_bf16 v[26:29], v[244:247], v[42:45], v[82:85]
	v_mfma_f32_16x16x32_bf16 v[118:121], v[198:201], v[30:33], v[98:101]
	v_mfma_f32_16x16x32_bf16 v[98:101], v[248:251], v[46:49], v[26:29]
	v_mfma_f32_16x16x32_bf16 v[26:29], v[150:153], v[182:185], v[170:173]
	v_mfma_f32_16x16x32_bf16 v[86:89], v[198:201], v[186:189], v[26:29]
	v_mfma_f32_16x16x32_bf16 v[26:29], v[244:247], v[182:185], v[174:177]
	v_mfma_f32_16x16x32_bf16 v[82:85], v[248:251], v[186:189], v[26:29]
	v_mfma_f32_16x16x32_bf16 v[26:29], v[150:153], v[190:193], v[70:73]
	v_mfma_f32_16x16x32_bf16 v[70:73], v[198:201], v[202:205], v[26:29]
	v_mfma_f32_16x16x32_bf16 v[26:29], v[244:247], v[190:193], v[66:69]
	v_mfma_f32_16x16x32_bf16 v[66:69], v[248:251], v[202:205], v[26:29]
	s_setprio 0
	s_barrier
	ds_read_b128 v[166:169], v134 offset:49152
	ds_read_b128 v[134:137], v134 offset:50176
	ds_read_b128 v[170:173], v133 offset:49152
	ds_read_b128 v[174:177], v133 offset:50176
	ds_read_b128 v[182:185], v132 offset:49152
	ds_read_b128 v[186:189], v132 offset:50176
	ds_read_b128 v[190:193], v131 offset:49152
	ds_read_b128 v[202:205], v131 offset:50176
	s_barrier
	s_waitcnt lgkmcnt(0)
	s_setprio 1
	v_mfma_f32_16x16x32_bf16 v[26:29], v[10:13], v[166:169], v[62:65]
	v_mfma_f32_16x16x32_bf16 v[62:65], v[14:17], v[134:137], v[26:29]
	v_mfma_f32_16x16x32_bf16 v[26:29], v[154:157], v[166:169], v[58:61]
	v_mfma_f32_16x16x32_bf16 v[58:61], v[178:181], v[134:137], v[26:29]
	v_mfma_f32_16x16x32_bf16 v[26:29], v[10:13], v[170:173], v[54:57]
	v_mfma_f32_16x16x32_bf16 v[46:49], v[14:17], v[174:177], v[26:29]
	v_mfma_f32_16x16x32_bf16 v[26:29], v[154:157], v[170:173], v[50:53]
	v_mfma_f32_16x16x32_bf16 v[42:45], v[178:181], v[174:177], v[26:29]
	v_mfma_f32_16x16x32_bf16 v[26:29], v[10:13], v[182:185], v[194:197]
	v_mfma_f32_16x16x32_bf16 v[10:13], v[10:13], v[190:193], v[38:41]
	v_mfma_f32_16x16x32_bf16 v[30:33], v[14:17], v[186:189], v[26:29]
	v_mfma_f32_16x16x32_bf16 v[26:29], v[154:157], v[182:185], v[240:243]
	v_mfma_f32_16x16x32_bf16 v[14:17], v[14:17], v[202:205], v[10:13]
	v_mfma_f32_16x16x32_bf16 v[10:13], v[154:157], v[190:193], v[34:37]
	v_mfma_f32_16x16x32_bf16 v[26:29], v[178:181], v[186:189], v[26:29]
	v_mfma_f32_16x16x32_bf16 v[10:13], v[178:181], v[202:205], v[10:13]
	s_setprio 0
	s_setprio 1
	v_mfma_f32_16x16x32_bf16 v[34:37], v[150:153], v[166:169], v[140:143]
	v_mfma_f32_16x16x32_bf16 v[54:57], v[198:201], v[134:137], v[34:37]
	v_mfma_f32_16x16x32_bf16 v[34:37], v[244:247], v[166:169], v[146:149]
	v_mfma_f32_16x16x32_bf16 v[18:21], v[244:247], v[170:173], v[18:21]
	v_mfma_f32_16x16x32_bf16 v[50:53], v[248:251], v[134:137], v[34:37]
	v_mfma_f32_16x16x32_bf16 v[22:25], v[150:153], v[170:173], v[22:25]
	v_mfma_f32_16x16x32_bf16 v[34:37], v[248:251], v[174:177], v[18:21]
	v_mfma_f32_16x16x32_bf16 v[18:21], v[150:153], v[182:185], v[158:161]
	v_mfma_f32_16x16x32_bf16 v[38:41], v[198:201], v[174:177], v[22:25]
	v_mfma_f32_16x16x32_bf16 v[22:25], v[198:201], v[186:189], v[18:21]
	v_mfma_f32_16x16x32_bf16 v[18:21], v[244:247], v[182:185], v[162:165]
	v_mfma_f32_16x16x32_bf16 v[6:9], v[150:153], v[190:193], v[6:9]
	v_mfma_f32_16x16x32_bf16 v[2:5], v[244:247], v[190:193], v[2:5]
	v_mfma_f32_16x16x32_bf16 v[18:21], v[248:251], v[186:189], v[18:21]
	v_mfma_f32_16x16x32_bf16 v[6:9], v[198:201], v[202:205], v[6:9]
	v_mfma_f32_16x16x32_bf16 v[2:5], v[248:251], v[202:205], v[2:5]
	s_setprio 0
	s_movk_i32 s4, 0x100
	v_cmp_gt_u32_e32 vcc, s4, v0
	s_barrier
	s_and_saveexec_b64 s[4:5], vcc
	s_cbranch_execz .LBB0_221
	s_barrier

; #define WAIT_V(n) asm volatile("s_waitcnt vmcnt(" #n ")" ::: "memory")
; #define WAIT_L(n) asm volatile("s_waitcnt lgkmcnt(" #n ")" ::: "memory")
; #define BAR __builtin_amdgcn_s_barrier()
; #define SCHED __builtin_amdgcn_sched_barrier(0)
; template <int MODE>
; __device__ __forceinline__ void gemm_tile(const int ph, const int which, const int pm, const int pn) {
;     ...
;     LDB(B0, 0, 0); SCHED; LDA(At, 0, 0); STAGE(SA(1, 1), RA, brow + HALF, t + 1);
;     WAIT_L(8); BAR; WAIT_L(0); MMA(0, 0, At, B0); BAR; SCHED;
;     LDB(B1, 0, 1); STAGE(SB(0, 0), RB, bcol, t + 2);
;     BAR; WAIT_L(0); MMA(0, 1, At, B1); BAR;
;     LDA(At, 0, 1); STAGE(SA(0, 0), RA, brow, t + 2);
;     BAR; WAIT_L(0); MMA(1, 0, At, B0); BAR; SCHED;
;     STAGE(SB(0, 1), RB, bcolB, t + 2);
;     WAIT_V(6); BAR; MMA(1, 1, At, B1); BAR;
.LBB0_370:
	ds_read_b128 v[156:159], v154
	ds_read_b128 v[168:171], v154 offset:1024
	ds_read_b128 v[172:175], v154 offset:2048
	ds_read_b128 v[176:179], v154 offset:3072
	s_add_i32 s12, s10, s21
	v_readfirstlane_b32 s23, v151
	s_add_i32 s13, s12, 0x80
	s_mov_b32 m0, s23
	ds_read_b128 v[180:183], v141
	ds_read_b128 v[184:187], v141 offset:1024
	ds_read_b128 v[188:191], v140
	ds_read_b128 v[192:195], v140 offset:1024
	ds_read_b128 v[196:199], v139
	ds_read_b128 v[200:203], v139 offset:1024
	ds_read_b128 v[204:207], v138
	ds_read_b128 v[236:239], v138 offset:1024
	buffer_load_dwordx4 v130, s[4:7], s13 offen lds
	s_add_i32 s13, s3, s21
	v_readfirstlane_b32 s27, v149
	s_add_i32 s23, s13, 0x80
	s_mov_b32 m0, s27
	s_nop 0
	buffer_load_dwordx4 v130, s[4:7], s23 offen lds
	s_waitcnt lgkmcnt(8)
	s_barrier
	s_waitcnt lgkmcnt(0)
	s_setprio 1
	v_mfma_f32_16x16x32_bf16 v[2:5], v[156:159], v[180:183], v[2:5]
	v_mfma_f32_16x16x32_bf16 v[6:9], v[172:175], v[180:183], v[6:9]
	v_mfma_f32_16x16x32_bf16 v[18:21], v[156:159], v[188:191], v[18:21]
	v_mfma_f32_16x16x32_bf16 v[30:33], v[172:175], v[188:191], v[30:33]
	v_mfma_f32_16x16x32_bf16 v[42:45], v[156:159], v[196:199], v[42:45]
	v_mfma_f32_16x16x32_bf16 v[54:57], v[172:175], v[196:199], v[54:57]
	v_mfma_f32_16x16x32_bf16 v[66:69], v[156:159], v[204:207], v[66:69]
	v_mfma_f32_16x16x32_bf16 v[78:81], v[172:175], v[204:207], v[78:81]
	v_mfma_f32_16x16x32_bf16 v[2:5], v[168:171], v[184:187], v[2:5]
	v_mfma_f32_16x16x32_bf16 v[6:9], v[176:179], v[184:187], v[6:9]
	v_mfma_f32_16x16x32_bf16 v[18:21], v[168:171], v[192:195], v[18:21]
	v_mfma_f32_16x16x32_bf16 v[30:33], v[176:179], v[192:195], v[30:33]
	v_mfma_f32_16x16x32_bf16 v[42:45], v[168:171], v[200:203], v[42:45]
	v_mfma_f32_16x16x32_bf16 v[54:57], v[176:179], v[200:203], v[54:57]
	v_mfma_f32_16x16x32_bf16 v[66:69], v[168:171], v[236:239], v[66:69]
	v_mfma_f32_16x16x32_bf16 v[78:81], v[176:179], v[236:239], v[78:81]
	s_setprio 0
	s_barrier
	s_add_i32 s23, s20, s21
	v_readfirstlane_b32 s28, v132
	s_add_i32 s27, s23, 0x100
	s_mov_b32 m0, s28
	ds_read_b128 v[240:243], v153
	ds_read_b128 v[244:247], v153 offset:1024
	ds_read_b128 v[248:251], v153 offset:2048
	ds_read_b128 v[210:213], v153 offset:3072
	buffer_load_dwordx4 v130, s[68:71], s27 offen lds
	s_add_i32 s27, s19, s21
	v_readfirstlane_b32 s29, v133
	s_add_i32 s28, s27, 0x100
	s_mov_b32 m0, s29
	s_add_i32 s22, s22, 2
	buffer_load_dwordx4 v130, s[68:71], s28 offen lds
	s_barrier
	s_waitcnt lgkmcnt(0)
	s_setprio 1
	v_mfma_f32_16x16x32_bf16 v[10:13], v[240:243], v[180:183], v[10:13]
	v_mfma_f32_16x16x32_bf16 v[22:25], v[248:251], v[180:183], v[22:25]
	v_mfma_f32_16x16x32_bf16 v[34:37], v[240:243], v[188:191], v[34:37]
	v_mfma_f32_16x16x32_bf16 v[46:49], v[248:251], v[188:191], v[46:49]
	v_mfma_f32_16x16x32_bf16 v[58:61], v[240:243], v[196:199], v[58:61]
	v_mfma_f32_16x16x32_bf16 v[70:73], v[248:251], v[196:199], v[70:73]
	v_mfma_f32_16x16x32_bf16 v[82:85], v[240:243], v[204:207], v[82:85]
	v_mfma_f32_16x16x32_bf16 v[94:97], v[248:251], v[204:207], v[94:97]
	v_mfma_f32_16x16x32_bf16 v[10:13], v[244:247], v[184:187], v[10:13]
	v_mfma_f32_16x16x32_bf16 v[22:25], v[210:213], v[184:187], v[22:25]
	v_mfma_f32_16x16x32_bf16 v[34:37], v[244:247], v[192:195], v[34:37]
	v_mfma_f32_16x16x32_bf16 v[46:49], v[210:213], v[192:195], v[46:49]
	v_mfma_f32_16x16x32_bf16 v[58:61], v[244:247], v[200:203], v[58:61]
	v_mfma_f32_16x16x32_bf16 v[70:73], v[210:213], v[200:203], v[70:73]
	v_mfma_f32_16x16x32_bf16 v[82:85], v[244:247], v[236:239], v[82:85]
	v_mfma_f32_16x16x32_bf16 v[94:97], v[210:213], v[236:239], v[94:97]
	s_setprio 0
	s_add_i32 s28, s18, s21
	v_readfirstlane_b32 s38, v131
	s_add_i32 s29, s28, 0x100
	s_mov_b32 m0, s38
	s_barrier
	ds_read_b128 v[180:183], v141 offset:16384
	ds_read_b128 v[184:187], v141 offset:17408
	ds_read_b128 v[188:191], v140 offset:16384
	ds_read_b128 v[192:195], v140 offset:17408
	ds_read_b128 v[196:199], v139 offset:16384
	ds_read_b128 v[200:203], v139 offset:17408
	ds_read_b128 v[204:207], v138 offset:16384
	ds_read_b128 v[236:239], v138 offset:17408
	buffer_load_dwordx4 v130, s[4:7], s29 offen lds
	s_add_i32 s29, s17, s21
	v_readfirstlane_b32 s43, v134
	s_add_i32 s38, s29, 0x100
	s_mov_b32 m0, s43
	s_nop 0
	buffer_load_dwordx4 v130, s[4:7], s38 offen lds
	s_barrier
	s_waitcnt lgkmcnt(0)
	s_setprio 1
	v_mfma_f32_16x16x32_bf16 v[14:17], v[156:159], v[180:183], v[14:17]
	v_mfma_f32_16x16x32_bf16 v[26:29], v[172:175], v[180:183], v[26:29]
	v_mfma_f32_16x16x32_bf16 v[38:41], v[156:159], v[188:191], v[38:41]
	v_mfma_f32_16x16x32_bf16 v[50:53], v[172:175], v[188:191], v[50:53]
	v_mfma_f32_16x16x32_bf16 v[62:65], v[156:159], v[196:199], v[62:65]
	v_mfma_f32_16x16x32_bf16 v[74:77], v[172:175], v[196:199], v[74:77]
	v_mfma_f32_16x16x32_bf16 v[86:89], v[156:159], v[204:207], v[86:89]
	v_mfma_f32_16x16x32_bf16 v[98:101], v[172:175], v[204:207], v[98:101]
	v_mfma_f32_16x16x32_bf16 v[14:17], v[168:171], v[184:187], v[14:17]
	v_mfma_f32_16x16x32_bf16 v[26:29], v[176:179], v[184:187], v[26:29]
	v_mfma_f32_16x16x32_bf16 v[38:41], v[168:171], v[192:195], v[38:41]
	v_mfma_f32_16x16x32_bf16 v[50:53], v[176:179], v[192:195], v[50:53]
	v_mfma_f32_16x16x32_bf16 v[62:65], v[168:171], v[200:203], v[62:65]
	v_mfma_f32_16x16x32_bf16 v[74:77], v[176:179], v[200:203], v[74:77]
	v_mfma_f32_16x16x32_bf16 v[86:89], v[168:171], v[236:239], v[86:89]
	v_mfma_f32_16x16x32_bf16 v[98:101], v[176:179], v[236:239], v[98:101]
	s_setprio 0
	s_barrier
	s_add_i32 s38, s16, s21
	v_readfirstlane_b32 s50, v135
	s_add_i32 s43, s38, 0x100
	s_mov_b32 m0, s50
	v_readfirstlane_b32 s51, v136
	buffer_load_dwordx4 v130, s[68:71], s43 offen lds
	s_add_i32 s43, s11, s21
	s_add_i32 s50, s43, 0x100
	s_mov_b32 m0, s51
	s_nop 0
	buffer_load_dwordx4 v130, s[68:71], s50 offen lds
	s_waitcnt vmcnt(6)
	s_barrier
; #define WAIT_V(n) asm volatile("s_waitcnt vmcnt(" #n ")" ::: "memory")
; #define WAIT_L(n) asm volatile("s_waitcnt lgkmcnt(" #n ")" ::: "memory")
; #define BAR __builtin_amdgcn_s_barrier()
; #define SCHED __builtin_amdgcn_sched_barrier(0)
; template <int MODE>
; __device__ __forceinline__ void gemm_tile(const int ph, const int which, const int pm, const int pn) {
;     ...
;     WAIT_V(6); BAR; MMA(1, 1, At, B1); BAR;
;     LDB(B0, 1, 0); SCHED; LDA(At, 1, 0); STAGE(SA(0, 1), RA, brow + HALF, t + 2);
;     WAIT_L(8); BAR; WAIT_L(0); MMA(0, 0, At, B0); BAR; SCHED;
;     LDB(B1, 1, 1); STAGE(SB(1, 0), RB, bcol, t + 3);
;     BAR; WAIT_L(0); MMA(0, 1, At, B1); BAR;
;     LDA(At, 1, 1); STAGE(SA(1, 0), RA, brow, t + 3);
	s_setprio 1
	v_mfma_f32_16x16x32_bf16 v[90:93], v[240:243], v[180:183], v[90:93]
	v_mfma_f32_16x16x32_bf16 v[102:105], v[248:251], v[180:183], v[102:105]
	v_mfma_f32_16x16x32_bf16 v[106:109], v[240:243], v[188:191], v[106:109]
	v_mfma_f32_16x16x32_bf16 v[110:113], v[248:251], v[188:191], v[110:113]
	v_mfma_f32_16x16x32_bf16 v[114:117], v[240:243], v[196:199], v[114:117]
	v_mfma_f32_16x16x32_bf16 v[118:121], v[248:251], v[196:199], v[118:121]
	v_mfma_f32_16x16x32_bf16 v[122:125], v[240:243], v[204:207], v[122:125]
	v_mfma_f32_16x16x32_bf16 v[126:129], v[248:251], v[204:207], v[126:129]
	v_mfma_f32_16x16x32_bf16 v[90:93], v[244:247], v[184:187], v[90:93]
	v_mfma_f32_16x16x32_bf16 v[102:105], v[210:213], v[184:187], v[102:105]
	v_mfma_f32_16x16x32_bf16 v[106:109], v[244:247], v[192:195], v[106:109]
	v_mfma_f32_16x16x32_bf16 v[110:113], v[210:213], v[192:195], v[110:113]
	v_mfma_f32_16x16x32_bf16 v[114:117], v[244:247], v[200:203], v[114:117]
	v_mfma_f32_16x16x32_bf16 v[118:121], v[210:213], v[200:203], v[118:121]
	v_mfma_f32_16x16x32_bf16 v[122:125], v[244:247], v[236:239], v[122:125]
	v_mfma_f32_16x16x32_bf16 v[126:129], v[210:213], v[236:239], v[126:129]
	s_setprio 0
	s_barrier
	ds_read_b128 v[156:159], v137
	ds_read_b128 v[168:171], v137 offset:1024
	ds_read_b128 v[172:175], v137 offset:2048
	ds_read_b128 v[176:179], v137 offset:3072
	v_readfirstlane_b32 s50, v143
	s_addk_i32 s12, 0x100
	s_mov_b32 m0, s50
	ds_read_b128 v[180:183], v141 offset:32768
	ds_read_b128 v[184:187], v141 offset:33792
	ds_read_b128 v[188:191], v140 offset:32768
	ds_read_b128 v[192:195], v140 offset:33792
	ds_read_b128 v[196:199], v139 offset:32768
	ds_read_b128 v[200:203], v139 offset:33792
	ds_read_b128 v[204:207], v138 offset:32768
	ds_read_b128 v[210:213], v138 offset:33792
	buffer_load_dwordx4 v130, s[4:7], s12 offen lds
	v_readfirstlane_b32 s12, v144
	s_addk_i32 s13, 0x100
	s_mov_b32 m0, s12
	s_nop 0
	buffer_load_dwordx4 v130, s[4:7], s13 offen lds
	s_waitcnt lgkmcnt(8)
	s_barrier
	s_waitcnt lgkmcnt(0)
	s_setprio 1
	v_mfma_f32_16x16x32_bf16 v[2:5], v[156:159], v[180:183], v[2:5]
	v_mfma_f32_16x16x32_bf16 v[6:9], v[172:175], v[180:183], v[6:9]
	v_mfma_f32_16x16x32_bf16 v[18:21], v[156:159], v[188:191], v[18:21]
	v_mfma_f32_16x16x32_bf16 v[30:33], v[172:175], v[188:191], v[30:33]
	v_mfma_f32_16x16x32_bf16 v[42:45], v[156:159], v[196:199], v[42:45]
	v_mfma_f32_16x16x32_bf16 v[54:57], v[172:175], v[196:199], v[54:57]
	v_mfma_f32_16x16x32_bf16 v[66:69], v[156:159], v[204:207], v[66:69]
	v_mfma_f32_16x16x32_bf16 v[78:81], v[172:175], v[204:207], v[78:81]
	v_mfma_f32_16x16x32_bf16 v[2:5], v[168:171], v[184:187], v[2:5]
	v_mfma_f32_16x16x32_bf16 v[6:9], v[176:179], v[184:187], v[6:9]
	v_mfma_f32_16x16x32_bf16 v[18:21], v[168:171], v[192:195], v[18:21]
	v_mfma_f32_16x16x32_bf16 v[30:33], v[176:179], v[192:195], v[30:33]
	v_mfma_f32_16x16x32_bf16 v[42:45], v[168:171], v[200:203], v[42:45]
	v_mfma_f32_16x16x32_bf16 v[54:57], v[176:179], v[200:203], v[54:57]
	v_mfma_f32_16x16x32_bf16 v[66:69], v[168:171], v[210:213], v[66:69]
	v_mfma_f32_16x16x32_bf16 v[78:81], v[176:179], v[210:213], v[78:81]
	s_setprio 0
	s_barrier
	v_readfirstlane_b32 s12, v145
	s_addk_i32 s23, 0x180
	s_mov_b32 m0, s12
	v_readfirstlane_b32 s12, v146
	ds_read_b128 v[236:239], v142
	ds_read_b128 v[240:243], v142 offset:1024
	ds_read_b128 v[244:247], v142 offset:2048
	ds_read_b128 v[248:251], v142 offset:3072
	buffer_load_dwordx4 v130, s[68:71], s23 offen lds
	s_addk_i32 s27, 0x180
	s_mov_b32 m0, s12
	s_nop 0
	buffer_load_dwordx4 v130, s[68:71], s27 offen lds
	s_barrier
	s_waitcnt lgkmcnt(0)
	s_setprio 1
	v_mfma_f32_16x16x32_bf16 v[10:13], v[236:239], v[180:183], v[10:13]
	v_mfma_f32_16x16x32_bf16 v[22:25], v[244:247], v[180:183], v[22:25]
	v_mfma_f32_16x16x32_bf16 v[34:37], v[236:239], v[188:191], v[34:37]
	v_mfma_f32_16x16x32_bf16 v[46:49], v[244:247], v[188:191], v[46:49]
	v_mfma_f32_16x16x32_bf16 v[58:61], v[236:239], v[196:199], v[58:61]
	v_mfma_f32_16x16x32_bf16 v[70:73], v[244:247], v[196:199], v[70:73]
	v_mfma_f32_16x16x32_bf16 v[82:85], v[236:239], v[204:207], v[82:85]
	v_mfma_f32_16x16x32_bf16 v[94:97], v[244:247], v[204:207], v[94:97]
	v_mfma_f32_16x16x32_bf16 v[10:13], v[240:243], v[184:187], v[10:13]
	v_mfma_f32_16x16x32_bf16 v[22:25], v[248:251], v[184:187], v[22:25]
	v_mfma_f32_16x16x32_bf16 v[34:37], v[240:243], v[192:195], v[34:37]
	v_mfma_f32_16x16x32_bf16 v[46:49], v[248:251], v[192:195], v[46:49]
	v_mfma_f32_16x16x32_bf16 v[58:61], v[240:243], v[200:203], v[58:61]
	v_mfma_f32_16x16x32_bf16 v[70:73], v[248:251], v[200:203], v[70:73]
	v_mfma_f32_16x16x32_bf16 v[82:85], v[240:243], v[210:213], v[82:85]
	v_mfma_f32_16x16x32_bf16 v[94:97], v[248:251], v[210:213], v[94:97]
	s_setprio 0
	v_readfirstlane_b32 s12, v147
	s_addk_i32 s28, 0x180
	s_mov_b32 m0, s12
	v_readfirstlane_b32 s12, v148
	s_barrier
	ds_read_b128 v[180:183], v141 offset:49152
	ds_read_b128 v[184:187], v141 offset:50176
	ds_read_b128 v[188:191], v140 offset:49152
	ds_read_b128 v[192:195], v140 offset:50176
	ds_read_b128 v[196:199], v139 offset:49152
	ds_read_b128 v[200:203], v139 offset:50176
	ds_read_b128 v[204:207], v138 offset:49152
	ds_read_b128 v[210:213], v138 offset:50176
	buffer_load_dwordx4 v130, s[4:7], s28 offen lds
	s_addk_i32 s29, 0x180
	s_mov_b32 m0, s12
	s_nop 0
	buffer_load_dwordx4 v130, s[4:7], s29 offen lds
	s_barrier
; #define WAIT_V(n) asm volatile("s_waitcnt vmcnt(" #n ")" ::: "memory")
; #define WAIT_L(n) asm volatile("s_waitcnt lgkmcnt(" #n ")" ::: "memory")
; #define BAR __builtin_amdgcn_s_barrier()
; #define SCHED __builtin_amdgcn_sched_barrier(0)
; template <int MODE>
; __device__ __forceinline__ void gemm_tile(const int ph, const int which, const int pm, const int pn) {
;     ...
;     BAR; WAIT_L(0); MMA(1, 0, At, B0); BAR; SCHED;
;     STAGE(SB(1, 1), RB, bcolB, t + 3);
;     WAIT_V(6); BAR; MMA(1, 1, At, B1); BAR;
;   }
;   {
;     LDB(B0, 0, 0); LDA(At, 0, 0); STAGE(SA(1, 1), RA, brow + HALF, nt - 1);
;     BAR; WAIT_L(0); MMA(0, 0, At, B0); BAR;
;     LDB(B1, 0, 1); BAR; WAIT_L(0); MMA(0, 1, At, B1); BAR;
	s_waitcnt lgkmcnt(0)
	s_setprio 1
	v_mfma_f32_16x16x32_bf16 v[14:17], v[156:159], v[180:183], v[14:17]
	v_mfma_f32_16x16x32_bf16 v[26:29], v[172:175], v[180:183], v[26:29]
	v_mfma_f32_16x16x32_bf16 v[38:41], v[156:159], v[188:191], v[38:41]
	v_mfma_f32_16x16x32_bf16 v[50:53], v[172:175], v[188:191], v[50:53]
	v_mfma_f32_16x16x32_bf16 v[62:65], v[156:159], v[196:199], v[62:65]
	v_mfma_f32_16x16x32_bf16 v[74:77], v[172:175], v[196:199], v[74:77]
	v_mfma_f32_16x16x32_bf16 v[86:89], v[156:159], v[204:207], v[86:89]
	v_mfma_f32_16x16x32_bf16 v[98:101], v[172:175], v[204:207], v[98:101]
	v_mfma_f32_16x16x32_bf16 v[14:17], v[168:171], v[184:187], v[14:17]
	v_mfma_f32_16x16x32_bf16 v[26:29], v[176:179], v[184:187], v[26:29]
	v_mfma_f32_16x16x32_bf16 v[38:41], v[168:171], v[192:195], v[38:41]
	v_mfma_f32_16x16x32_bf16 v[50:53], v[176:179], v[192:195], v[50:53]
	v_mfma_f32_16x16x32_bf16 v[62:65], v[168:171], v[200:203], v[62:65]
	v_mfma_f32_16x16x32_bf16 v[74:77], v[176:179], v[200:203], v[74:77]
	v_mfma_f32_16x16x32_bf16 v[86:89], v[168:171], v[210:213], v[86:89]
	v_mfma_f32_16x16x32_bf16 v[98:101], v[176:179], v[210:213], v[98:101]
	s_setprio 0
	s_barrier
	v_readfirstlane_b32 s12, v150
	s_addk_i32 s38, 0x180
	s_mov_b32 m0, s12
	v_readfirstlane_b32 s12, v152
	buffer_load_dwordx4 v130, s[68:71], s38 offen lds
	s_addk_i32 s43, 0x180
	s_mov_b32 m0, s12
	s_nop 0
	buffer_load_dwordx4 v130, s[68:71], s43 offen lds
	s_waitcnt vmcnt(6)
	s_barrier
	s_setprio 1
	v_mfma_f32_16x16x32_bf16 v[90:93], v[236:239], v[180:183], v[90:93]
	v_mfma_f32_16x16x32_bf16 v[102:105], v[244:247], v[180:183], v[102:105]
	v_mfma_f32_16x16x32_bf16 v[106:109], v[236:239], v[188:191], v[106:109]
	v_mfma_f32_16x16x32_bf16 v[110:113], v[244:247], v[188:191], v[110:113]
	v_mfma_f32_16x16x32_bf16 v[114:117], v[236:239], v[196:199], v[114:117]
	v_mfma_f32_16x16x32_bf16 v[118:121], v[244:247], v[196:199], v[118:121]
	v_mfma_f32_16x16x32_bf16 v[122:125], v[236:239], v[204:207], v[122:125]
	v_mfma_f32_16x16x32_bf16 v[126:129], v[244:247], v[204:207], v[126:129]
	v_mfma_f32_16x16x32_bf16 v[90:93], v[240:243], v[184:187], v[90:93]
	v_mfma_f32_16x16x32_bf16 v[102:105], v[248:251], v[184:187], v[102:105]
	v_mfma_f32_16x16x32_bf16 v[106:109], v[240:243], v[192:195], v[106:109]
	v_mfma_f32_16x16x32_bf16 v[110:113], v[248:251], v[192:195], v[110:113]
	v_mfma_f32_16x16x32_bf16 v[114:117], v[240:243], v[200:203], v[114:117]
	v_mfma_f32_16x16x32_bf16 v[118:121], v[248:251], v[200:203], v[118:121]
	v_mfma_f32_16x16x32_bf16 v[122:125], v[240:243], v[210:213], v[122:125]
	v_mfma_f32_16x16x32_bf16 v[126:129], v[248:251], v[210:213], v[126:129]
	s_setprio 0
	s_addk_i32 s21, 0x100
	s_cmp_lt_u32 s22, s2
	s_barrier
	s_cbranch_scc1 .LBB0_370
	s_add_i32 s2, s26, s9
	s_lshl_b32 s2, s2, 1
	v_readfirstlane_b32 s3, v151
	s_addk_i32 s2, 0xff80
	s_mov_b32 s6, s70
	s_mov_b32 s7, s71
	s_mov_b32 m0, s3
	v_readfirstlane_b32 s3, v149
	ds_read_b128 v[132:135], v154
	ds_read_b128 v[144:147], v154 offset:1024
	ds_read_b128 v[156:159], v154 offset:2048
	ds_read_b128 v[168:171], v154 offset:3072
	ds_read_b128 v[172:175], v141
	ds_read_b128 v[176:179], v141 offset:1024
	ds_read_b128 v[180:183], v140
	ds_read_b128 v[184:187], v140 offset:1024
	ds_read_b128 v[188:191], v139
	ds_read_b128 v[192:195], v139 offset:1024
	ds_read_b128 v[196:199], v138
	ds_read_b128 v[200:203], v138 offset:1024
	buffer_load_dwordx4 v130, s[4:7], s2 offen lds
	s_add_i32 s2, s2, s8
	s_mov_b32 m0, s3
	s_nop 0
	buffer_load_dwordx4 v130, s[4:7], s2 offen lds
	s_barrier
	s_waitcnt lgkmcnt(0)
	s_setprio 1
	v_mfma_f32_16x16x32_bf16 v[2:5], v[132:135], v[172:175], v[2:5]
	v_mfma_f32_16x16x32_bf16 v[6:9], v[156:159], v[172:175], v[6:9]
	v_mfma_f32_16x16x32_bf16 v[18:21], v[132:135], v[180:183], v[18:21]
	v_mfma_f32_16x16x32_bf16 v[66:69], v[132:135], v[196:199], v[66:69]
	v_mfma_f32_16x16x32_bf16 v[78:81], v[156:159], v[196:199], v[78:81]
	v_mfma_f32_16x16x32_bf16 v[2:5], v[144:147], v[176:179], v[2:5]
	v_mfma_f32_16x16x32_bf16 v[6:9], v[168:171], v[176:179], v[6:9]
	v_mfma_f32_16x16x32_bf16 v[18:21], v[144:147], v[184:187], v[18:21]
	v_mfma_f32_16x16x32_bf16 v[30:33], v[156:159], v[180:183], v[30:33]
	v_mfma_f32_16x16x32_bf16 v[42:45], v[132:135], v[188:191], v[42:45]
	v_mfma_f32_16x16x32_bf16 v[54:57], v[156:159], v[188:191], v[54:57]
	v_mfma_f32_16x16x32_bf16 v[66:69], v[144:147], v[200:203], v[66:69]
	v_mfma_f32_16x16x32_bf16 v[78:81], v[168:171], v[200:203], v[78:81]
	v_mfma_f32_16x16x32_bf16 v[30:33], v[168:171], v[184:187], v[30:33]
	v_mfma_f32_16x16x32_bf16 v[42:45], v[144:147], v[192:195], v[42:45]
	v_mfma_f32_16x16x32_bf16 v[54:57], v[168:171], v[192:195], v[54:57]
	s_setprio 0
	s_barrier
	ds_read_b128 v[148:151], v153
	ds_read_b128 v[204:207], v153 offset:1024
	ds_read_b128 v[210:213], v153 offset:2048
	ds_read_b128 v[152:155], v153 offset:3072
	s_barrier
	s_waitcnt lgkmcnt(0)
	s_setprio 1
	v_mfma_f32_16x16x32_bf16 v[10:13], v[148:151], v[172:175], v[10:13]
	v_mfma_f32_16x16x32_bf16 v[22:25], v[210:213], v[172:175], v[22:25]
	v_mfma_f32_16x16x32_bf16 v[58:61], v[148:151], v[188:191], v[58:61]
	v_mfma_f32_16x16x32_bf16 v[70:73], v[210:213], v[188:191], v[70:73]
	v_mfma_f32_16x16x32_bf16 v[82:85], v[148:151], v[196:199], v[82:85]
	v_mfma_f32_16x16x32_bf16 v[10:13], v[204:207], v[176:179], v[10:13]
	v_mfma_f32_16x16x32_bf16 v[22:25], v[152:155], v[176:179], v[22:25]
	v_mfma_f32_16x16x32_bf16 v[34:37], v[148:151], v[180:183], v[34:37]
	v_mfma_f32_16x16x32_bf16 v[46:49], v[210:213], v[180:183], v[46:49]
	v_mfma_f32_16x16x32_bf16 v[58:61], v[204:207], v[192:195], v[58:61]
	v_mfma_f32_16x16x32_bf16 v[70:73], v[152:155], v[192:195], v[70:73]
	v_mfma_f32_16x16x32_bf16 v[172:175], v[204:207], v[200:203], v[82:85]
	v_mfma_f32_16x16x32_bf16 v[82:85], v[210:213], v[196:199], v[94:97]
	v_mfma_f32_16x16x32_bf16 v[34:37], v[204:207], v[184:187], v[34:37]
	v_mfma_f32_16x16x32_bf16 v[46:49], v[152:155], v[184:187], v[46:49]
	v_mfma_f32_16x16x32_bf16 v[176:179], v[152:155], v[200:203], v[82:85]
	s_setprio 0
	s_barrier
; #define WAIT_V(n) asm volatile("s_waitcnt vmcnt(" #n ")" ::: "memory")
; #define WAIT_L(n) asm volatile("s_waitcnt lgkmcnt(" #n ")" ::: "memory")
; #define BAR __builtin_amdgcn_s_barrier()
; template <int MODE>
; __device__ __forceinline__ void gemm_tile(const int ph, const int which, const int pm, const int pn) {
;     ...
;     LDA(At, 0, 1); WAIT_V(4); BAR; WAIT_L(0); MMA(1, 0, At, B0); MMA(1, 1, At, B1); BAR;
;   }
;   {
;     LDB(B0, 1, 0); LDA(At, 1, 0); WAIT_V(2); BAR; WAIT_L(0); MMA(0, 0, At, B0); BAR;
	s_nop 2
	ds_read_b128 v[82:85], v141 offset:16384
	ds_read_b128 v[94:97], v141 offset:17408
	ds_read_b128 v[180:183], v140 offset:16384
	ds_read_b128 v[184:187], v140 offset:17408
	ds_read_b128 v[188:191], v139 offset:16384
	ds_read_b128 v[192:195], v139 offset:17408
	ds_read_b128 v[196:199], v138 offset:16384
	ds_read_b128 v[200:203], v138 offset:17408
	s_waitcnt vmcnt(4)
	s_barrier
	s_waitcnt lgkmcnt(0)
	s_setprio 1
	v_mfma_f32_16x16x32_bf16 v[74:77], v[156:159], v[188:191], v[74:77]
	v_mfma_f32_16x16x32_bf16 v[236:239], v[168:171], v[192:195], v[74:77]
	v_mfma_f32_16x16x32_bf16 v[74:77], v[132:135], v[196:199], v[86:89]
	v_mfma_f32_16x16x32_bf16 v[14:17], v[132:135], v[82:85], v[14:17]
	v_mfma_f32_16x16x32_bf16 v[62:65], v[132:135], v[188:191], v[62:65]
	v_mfma_f32_16x16x32_bf16 v[240:243], v[144:147], v[200:203], v[74:77]
	v_mfma_f32_16x16x32_bf16 v[74:77], v[156:159], v[196:199], v[98:101]
	v_mfma_f32_16x16x32_bf16 v[14:17], v[144:147], v[94:97], v[14:17]
	v_mfma_f32_16x16x32_bf16 v[26:29], v[156:159], v[82:85], v[26:29]
	v_mfma_f32_16x16x32_bf16 v[38:41], v[132:135], v[180:183], v[38:41]
	v_mfma_f32_16x16x32_bf16 v[50:53], v[156:159], v[180:183], v[50:53]
	v_mfma_f32_16x16x32_bf16 v[62:65], v[144:147], v[192:195], v[62:65]
	v_mfma_f32_16x16x32_bf16 v[98:101], v[168:171], v[200:203], v[74:77]
	v_mfma_f32_16x16x32_bf16 v[26:29], v[168:171], v[94:97], v[26:29]
	v_mfma_f32_16x16x32_bf16 v[38:41], v[144:147], v[184:187], v[38:41]
	v_mfma_f32_16x16x32_bf16 v[50:53], v[168:171], v[184:187], v[50:53]
	s_setprio 0
	s_setprio 1
	v_mfma_f32_16x16x32_bf16 v[74:77], v[148:151], v[82:85], v[90:93]
	v_mfma_f32_16x16x32_bf16 v[168:171], v[204:207], v[94:97], v[74:77]
	v_mfma_f32_16x16x32_bf16 v[74:77], v[210:213], v[82:85], v[102:105]
	v_mfma_f32_16x16x32_bf16 v[244:247], v[152:155], v[94:97], v[74:77]
	v_mfma_f32_16x16x32_bf16 v[74:77], v[148:151], v[180:183], v[106:109]
	v_mfma_f32_16x16x32_bf16 v[248:251], v[204:207], v[184:187], v[74:77]
	v_mfma_f32_16x16x32_bf16 v[74:77], v[210:213], v[180:183], v[110:113]
	v_mfma_f32_16x16x32_bf16 v[180:183], v[152:155], v[184:187], v[74:77]
	v_mfma_f32_16x16x32_bf16 v[74:77], v[148:151], v[188:191], v[114:117]
	v_mfma_f32_16x16x32_bf16 v[184:187], v[204:207], v[192:195], v[74:77]
	v_mfma_f32_16x16x32_bf16 v[74:77], v[210:213], v[188:191], v[118:121]
	v_mfma_f32_16x16x32_bf16 v[188:191], v[152:155], v[192:195], v[74:77]
	v_mfma_f32_16x16x32_bf16 v[74:77], v[148:151], v[196:199], v[122:125]
	v_mfma_f32_16x16x32_bf16 v[192:195], v[204:207], v[200:203], v[74:77]
	v_mfma_f32_16x16x32_bf16 v[74:77], v[210:213], v[196:199], v[126:129]
	v_mfma_f32_16x16x32_bf16 v[196:199], v[152:155], v[200:203], v[74:77]
	s_setprio 0
	s_barrier
	ds_read_b128 v[102:105], v137
	ds_read_b128 v[200:203], v137 offset:1024
	ds_read_b128 v[204:207], v137 offset:2048
	ds_read_b128 v[210:213], v137 offset:3072
	s_nop 0
	ds_read_b128 v[74:77], v141 offset:32768
	ds_read_b128 v[82:85], v141 offset:33792
	ds_read_b128 v[144:147], v140 offset:32768
	ds_read_b128 v[148:151], v140 offset:33792
	ds_read_b128 v[152:155], v139 offset:32768
	ds_read_b128 v[156:159], v139 offset:33792
	ds_read_b128 v[218:221], v138 offset:32768
	ds_read_b128 v[230:233], v138 offset:33792
	s_waitcnt vmcnt(2)
	s_barrier
	s_waitcnt lgkmcnt(0)
	s_setprio 1
	v_mfma_f32_16x16x32_bf16 v[2:5], v[102:105], v[74:77], v[2:5]
	v_mfma_f32_16x16x32_bf16 v[106:109], v[200:203], v[82:85], v[2:5]
	v_mfma_f32_16x16x32_bf16 v[2:5], v[204:207], v[74:77], v[6:9]
	v_mfma_f32_16x16x32_bf16 v[110:113], v[210:213], v[82:85], v[2:5]
	v_mfma_f32_16x16x32_bf16 v[2:5], v[102:105], v[144:147], v[18:21]
	v_mfma_f32_16x16x32_bf16 v[114:117], v[200:203], v[148:151], v[2:5]
	v_mfma_f32_16x16x32_bf16 v[2:5], v[204:207], v[144:147], v[30:33]
	v_mfma_f32_16x16x32_bf16 v[118:121], v[210:213], v[148:151], v[2:5]
	v_mfma_f32_16x16x32_bf16 v[2:5], v[102:105], v[152:155], v[42:45]
	v_mfma_f32_16x16x32_bf16 v[122:125], v[200:203], v[156:159], v[2:5]
	v_mfma_f32_16x16x32_bf16 v[2:5], v[204:207], v[152:155], v[54:57]
	v_mfma_f32_16x16x32_bf16 v[126:129], v[210:213], v[156:159], v[2:5]
	v_mfma_f32_16x16x32_bf16 v[2:5], v[102:105], v[218:221], v[66:69]
	v_mfma_f32_16x16x32_bf16 v[130:133], v[200:203], v[230:233], v[2:5]
	v_mfma_f32_16x16x32_bf16 v[2:5], v[204:207], v[218:221], v[78:81]
	v_mfma_f32_16x16x32_bf16 v[134:137], v[210:213], v[230:233], v[2:5]
	s_setprio 0
	s_barrier
; #define WAIT_V(n) asm volatile("s_waitcnt vmcnt(" #n ")" ::: "memory")
; #define WAIT_L(n) asm volatile("s_waitcnt lgkmcnt(" #n ")" ::: "memory")
; #define BAR __builtin_amdgcn_s_barrier()
; template <int MODE>
; __device__ __forceinline__ void gemm_tile(const int ph, const int which, const int pm, const int pn) {
;     ...
;     LDB(B1, 1, 1); WAIT_V(0); BAR; WAIT_L(0); MMA(0, 1, At, B1); BAR;
;     LDA(At, 1, 1); BAR; WAIT_L(0); MMA(1, 0, At, B0); MMA(1, 1, At, B1); BAR;
;   }
;   if (wr == 0) BAR;
	s_nop 4
	ds_read_b128 v[2:5], v142
	ds_read_b128 v[6:9], v142 offset:1024
	ds_read_b128 v[30:33], v142 offset:2048
	ds_read_b128 v[42:45], v142 offset:3072
	s_waitcnt vmcnt(0)
	s_barrier
	s_waitcnt lgkmcnt(0)
	s_setprio 1
	v_mfma_f32_16x16x32_bf16 v[10:13], v[2:5], v[74:77], v[10:13]
	v_mfma_f32_16x16x32_bf16 v[94:97], v[6:9], v[82:85], v[10:13]
	v_mfma_f32_16x16x32_bf16 v[10:13], v[30:33], v[74:77], v[22:25]
	v_mfma_f32_16x16x32_bf16 v[90:93], v[42:45], v[82:85], v[10:13]
	v_mfma_f32_16x16x32_bf16 v[10:13], v[2:5], v[144:147], v[34:37]
	v_mfma_f32_16x16x32_bf16 v[86:89], v[6:9], v[148:151], v[10:13]
	v_mfma_f32_16x16x32_bf16 v[10:13], v[30:33], v[144:147], v[46:49]
	v_mfma_f32_16x16x32_bf16 v[82:85], v[42:45], v[148:151], v[10:13]
	v_mfma_f32_16x16x32_bf16 v[10:13], v[2:5], v[152:155], v[58:61]
	v_mfma_f32_16x16x32_bf16 v[78:81], v[6:9], v[156:159], v[10:13]
	v_mfma_f32_16x16x32_bf16 v[10:13], v[30:33], v[152:155], v[70:73]
	v_mfma_f32_16x16x32_bf16 v[74:77], v[42:45], v[156:159], v[10:13]
	v_mfma_f32_16x16x32_bf16 v[10:13], v[2:5], v[218:221], v[172:175]
	v_mfma_f32_16x16x32_bf16 v[70:73], v[6:9], v[230:233], v[10:13]
	v_mfma_f32_16x16x32_bf16 v[10:13], v[30:33], v[218:221], v[176:179]
	v_mfma_f32_16x16x32_bf16 v[66:69], v[42:45], v[230:233], v[10:13]
	s_setprio 0
	s_barrier
	s_nop 4
	ds_read_b128 v[10:13], v141 offset:49152
	ds_read_b128 v[18:21], v141 offset:50176
	ds_read_b128 v[34:37], v140 offset:49152
	ds_read_b128 v[46:49], v140 offset:50176
	ds_read_b128 v[54:57], v139 offset:49152
	ds_read_b128 v[172:175], v139 offset:50176
	ds_read_b128 v[176:179], v138 offset:49152
	ds_read_b128 v[218:221], v138 offset:50176
	s_barrier
	s_waitcnt lgkmcnt(0)
	s_setprio 1
	v_mfma_f32_16x16x32_bf16 v[14:17], v[102:105], v[10:13], v[14:17]
	v_mfma_f32_16x16x32_bf16 v[158:161], v[200:203], v[18:21], v[14:17]
	v_mfma_f32_16x16x32_bf16 v[14:17], v[204:207], v[10:13], v[26:29]
	v_mfma_f32_16x16x32_bf16 v[154:157], v[210:213], v[18:21], v[14:17]
	v_mfma_f32_16x16x32_bf16 v[14:17], v[102:105], v[34:37], v[38:41]
	v_mfma_f32_16x16x32_bf16 v[150:153], v[200:203], v[46:49], v[14:17]
	v_mfma_f32_16x16x32_bf16 v[14:17], v[204:207], v[34:37], v[50:53]
	v_mfma_f32_16x16x32_bf16 v[146:149], v[210:213], v[46:49], v[14:17]
	v_mfma_f32_16x16x32_bf16 v[14:17], v[102:105], v[54:57], v[62:65]
	v_mfma_f32_16x16x32_bf16 v[142:145], v[200:203], v[172:175], v[14:17]
	v_mfma_f32_16x16x32_bf16 v[14:17], v[204:207], v[54:57], v[236:239]
	v_mfma_f32_16x16x32_bf16 v[138:141], v[210:213], v[172:175], v[14:17]
	v_mfma_f32_16x16x32_bf16 v[14:17], v[102:105], v[176:179], v[240:243]
	v_mfma_f32_16x16x32_bf16 v[102:105], v[200:203], v[218:221], v[14:17]
	v_mfma_f32_16x16x32_bf16 v[14:17], v[204:207], v[176:179], v[98:101]
	v_mfma_f32_16x16x32_bf16 v[98:101], v[210:213], v[218:221], v[14:17]
	s_setprio 0
	s_setprio 1
	v_mfma_f32_16x16x32_bf16 v[14:17], v[2:5], v[10:13], v[168:171]
	v_mfma_f32_16x16x32_bf16 v[10:13], v[30:33], v[10:13], v[244:247]
	v_mfma_f32_16x16x32_bf16 v[58:61], v[42:45], v[18:21], v[10:13]
	v_mfma_f32_16x16x32_bf16 v[10:13], v[2:5], v[34:37], v[248:251]
	v_mfma_f32_16x16x32_bf16 v[22:25], v[6:9], v[46:49], v[10:13]
	v_mfma_f32_16x16x32_bf16 v[10:13], v[30:33], v[34:37], v[180:183]
	v_mfma_f32_16x16x32_bf16 v[62:65], v[6:9], v[18:21], v[14:17]
	v_mfma_f32_16x16x32_bf16 v[18:21], v[42:45], v[46:49], v[10:13]
	v_mfma_f32_16x16x32_bf16 v[10:13], v[2:5], v[54:57], v[184:187]
	v_mfma_f32_16x16x32_bf16 v[2:5], v[2:5], v[176:179], v[192:195]
	v_mfma_f32_16x16x32_bf16 v[14:17], v[6:9], v[172:175], v[10:13]
	v_mfma_f32_16x16x32_bf16 v[10:13], v[30:33], v[54:57], v[188:191]
	v_mfma_f32_16x16x32_bf16 v[6:9], v[6:9], v[218:221], v[2:5]
	v_mfma_f32_16x16x32_bf16 v[2:5], v[30:33], v[176:179], v[196:199]
	v_mfma_f32_16x16x32_bf16 v[10:13], v[42:45], v[172:175], v[10:13]
	v_mfma_f32_16x16x32_bf16 v[2:5], v[42:45], v[218:221], v[2:5]
	s_setprio 0
	s_movk_i32 s2, 0x100
	v_cmp_gt_u32_e32 vcc, s2, v164
	s_barrier
	s_and_saveexec_b64 s[2:3], vcc
	s_cbranch_execz .LBB0_373
	s_barrier

; #define WAIT_L(n) asm volatile("s_waitcnt lgkmcnt(" #n ")" ::: "memory")
; #define BAR __builtin_amdgcn_s_barrier()
; #define SCHED __builtin_amdgcn_sched_barrier(0)
; template <int MODE>
; __device__ __forceinline__ void gemm_tile(const int ph, const int which, const int pm, const int pn) {
;     ...
;     LDB(B0, 0, 0); SCHED; LDA(At, 0, 0); STAGE(SA(1, 1), RA, brow + HALF, t + 1);
;     WAIT_L(8); BAR; WAIT_L(0); MMA(0, 0, At, B0); BAR; SCHED;
;     LDB(B1, 0, 1); STAGE(SB(0, 0), RB, bcol, t + 2);
;     BAR; WAIT_L(0); MMA(0, 1, At, B1); BAR;
;     LDA(At, 0, 1); STAGE(SA(0, 0), RA, brow, t + 2);
;     BAR; WAIT_L(0); MMA(1, 0, At, B0); BAR; SCHED;
.LBB0_540:
	ds_read_b128 v[158:161], v156
	ds_read_b128 v[162:165], v156 offset:1024
	ds_read_b128 v[166:169], v156 offset:2048
	ds_read_b128 v[170:173], v156 offset:3072
	s_add_i32 s26, s10, s23
	v_readfirstlane_b32 s28, v153
	s_add_i32 s27, s26, 0x80
	s_mov_b32 m0, s28
	ds_read_b128 v[174:177], v135
	ds_read_b128 v[178:181], v135 offset:1024
	ds_read_b128 v[182:185], v134
	ds_read_b128 v[186:189], v134 offset:1024
	ds_read_b128 v[190:193], v133
	ds_read_b128 v[194:197], v133 offset:1024
	ds_read_b128 v[198:201], v132
	ds_read_b128 v[202:205], v132 offset:1024
	buffer_load_dwordx4 v136, s[4:7], s27 offen lds
	s_add_i32 s27, s3, s23
	v_readfirstlane_b32 s51, v151
	s_add_i32 s28, s27, 0x80
	s_mov_b32 m0, s51
	s_nop 0
	buffer_load_dwordx4 v136, s[4:7], s28 offen lds
	s_waitcnt lgkmcnt(8)
	s_barrier
	s_waitcnt lgkmcnt(0)
	s_setprio 1
	v_mfma_f32_16x16x32_bf16 v[126:129], v[158:161], v[174:177], v[126:129]
	v_mfma_f32_16x16x32_bf16 v[122:125], v[166:169], v[174:177], v[122:125]
	v_mfma_f32_16x16x32_bf16 v[118:121], v[158:161], v[182:185], v[118:121]
	v_mfma_f32_16x16x32_bf16 v[114:117], v[166:169], v[182:185], v[114:117]
	v_mfma_f32_16x16x32_bf16 v[110:113], v[158:161], v[190:193], v[110:113]
	v_mfma_f32_16x16x32_bf16 v[106:109], v[166:169], v[190:193], v[106:109]
	v_mfma_f32_16x16x32_bf16 v[102:105], v[158:161], v[198:201], v[102:105]
	v_mfma_f32_16x16x32_bf16 v[98:101], v[166:169], v[198:201], v[98:101]
	v_mfma_f32_16x16x32_bf16 v[126:129], v[162:165], v[178:181], v[126:129]
	v_mfma_f32_16x16x32_bf16 v[122:125], v[170:173], v[178:181], v[122:125]
	v_mfma_f32_16x16x32_bf16 v[118:121], v[162:165], v[186:189], v[118:121]
	v_mfma_f32_16x16x32_bf16 v[114:117], v[170:173], v[186:189], v[114:117]
	v_mfma_f32_16x16x32_bf16 v[110:113], v[162:165], v[194:197], v[110:113]
	v_mfma_f32_16x16x32_bf16 v[106:109], v[170:173], v[194:197], v[106:109]
	v_mfma_f32_16x16x32_bf16 v[102:105], v[162:165], v[202:205], v[102:105]
	v_mfma_f32_16x16x32_bf16 v[98:101], v[170:173], v[202:205], v[98:101]
	s_setprio 0
	s_barrier
	s_add_i32 s28, s22, s23
	v_readfirstlane_b32 s84, v139
	s_add_i32 s51, s28, 0x100
	s_mov_b32 m0, s84
	ds_read_b128 v[236:239], v155
	ds_read_b128 v[240:243], v155 offset:1024
	ds_read_b128 v[244:247], v155 offset:2048
	ds_read_b128 v[248:251], v155 offset:3072
	buffer_load_dwordx4 v136, s[68:71], s51 offen lds
	s_add_i32 s51, s21, s23
	v_readfirstlane_b32 s50, v140
	s_add_i32 s84, s51, 0x100
	s_mov_b32 m0, s50
	s_add_i32 s25, s25, 2
	buffer_load_dwordx4 v136, s[68:71], s84 offen lds
	s_barrier
	s_waitcnt lgkmcnt(0)
	s_setprio 1
	v_mfma_f32_16x16x32_bf16 v[94:97], v[236:239], v[174:177], v[94:97]
	v_mfma_f32_16x16x32_bf16 v[90:93], v[244:247], v[174:177], v[90:93]
	v_mfma_f32_16x16x32_bf16 v[86:89], v[236:239], v[182:185], v[86:89]
	v_mfma_f32_16x16x32_bf16 v[82:85], v[244:247], v[182:185], v[82:85]
	v_mfma_f32_16x16x32_bf16 v[78:81], v[236:239], v[190:193], v[78:81]
	v_mfma_f32_16x16x32_bf16 v[74:77], v[244:247], v[190:193], v[74:77]
	v_mfma_f32_16x16x32_bf16 v[70:73], v[236:239], v[198:201], v[70:73]
	v_mfma_f32_16x16x32_bf16 v[66:69], v[244:247], v[198:201], v[66:69]
	v_mfma_f32_16x16x32_bf16 v[94:97], v[240:243], v[178:181], v[94:97]
	v_mfma_f32_16x16x32_bf16 v[90:93], v[248:251], v[178:181], v[90:93]
	v_mfma_f32_16x16x32_bf16 v[86:89], v[240:243], v[186:189], v[86:89]
	v_mfma_f32_16x16x32_bf16 v[82:85], v[248:251], v[186:189], v[82:85]
	v_mfma_f32_16x16x32_bf16 v[78:81], v[240:243], v[194:197], v[78:81]
	v_mfma_f32_16x16x32_bf16 v[74:77], v[248:251], v[194:197], v[74:77]
	v_mfma_f32_16x16x32_bf16 v[70:73], v[240:243], v[202:205], v[70:73]
	v_mfma_f32_16x16x32_bf16 v[66:69], v[248:251], v[202:205], v[66:69]
	s_setprio 0
	s_add_i32 s50, s20, s23
	v_readfirstlane_b32 s29, v137
	s_add_i32 s84, s50, 0x100
	s_mov_b32 m0, s29
	s_add_i32 s29, s19, s23
	v_readfirstlane_b32 s43, v141
	s_barrier
	ds_read_b128 v[174:177], v135 offset:16384
	ds_read_b128 v[178:181], v135 offset:17408
	ds_read_b128 v[182:185], v134 offset:16384
	ds_read_b128 v[186:189], v134 offset:17408
	ds_read_b128 v[190:193], v133 offset:16384
	ds_read_b128 v[194:197], v133 offset:17408
	ds_read_b128 v[198:201], v132 offset:16384
	ds_read_b128 v[202:205], v132 offset:17408
	buffer_load_dwordx4 v136, s[4:7], s84 offen lds
	s_add_i32 s84, s29, 0x100
	s_mov_b32 m0, s43
	s_nop 0
	buffer_load_dwordx4 v136, s[4:7], s84 offen lds
	s_barrier
	s_waitcnt lgkmcnt(0)
	s_setprio 1
	v_mfma_f32_16x16x32_bf16 v[62:65], v[158:161], v[174:177], v[62:65]
	v_mfma_f32_16x16x32_bf16 v[58:61], v[166:169], v[174:177], v[58:61]
	v_mfma_f32_16x16x32_bf16 v[54:57], v[158:161], v[182:185], v[54:57]
	v_mfma_f32_16x16x32_bf16 v[50:53], v[166:169], v[182:185], v[50:53]
	v_mfma_f32_16x16x32_bf16 v[46:49], v[158:161], v[190:193], v[46:49]
	v_mfma_f32_16x16x32_bf16 v[42:45], v[166:169], v[190:193], v[42:45]
	v_mfma_f32_16x16x32_bf16 v[38:41], v[158:161], v[198:201], v[38:41]
	v_mfma_f32_16x16x32_bf16 v[34:37], v[166:169], v[198:201], v[34:37]
	v_mfma_f32_16x16x32_bf16 v[62:65], v[162:165], v[178:181], v[62:65]
	v_mfma_f32_16x16x32_bf16 v[58:61], v[170:173], v[178:181], v[58:61]
	v_mfma_f32_16x16x32_bf16 v[54:57], v[162:165], v[186:189], v[54:57]
	v_mfma_f32_16x16x32_bf16 v[50:53], v[170:173], v[186:189], v[50:53]
	v_mfma_f32_16x16x32_bf16 v[46:49], v[162:165], v[194:197], v[46:49]
	v_mfma_f32_16x16x32_bf16 v[42:45], v[170:173], v[194:197], v[42:45]
	v_mfma_f32_16x16x32_bf16 v[38:41], v[162:165], v[202:205], v[38:41]
	v_mfma_f32_16x16x32_bf16 v[34:37], v[170:173], v[202:205], v[34:37]
	s_setprio 0
	s_barrier
; #define WAIT_V(n) asm volatile("s_waitcnt vmcnt(" #n ")" ::: "memory")
; #define WAIT_L(n) asm volatile("s_waitcnt lgkmcnt(" #n ")" ::: "memory")
; #define BAR __builtin_amdgcn_s_barrier()
; #define SCHED __builtin_amdgcn_sched_barrier(0)
; template <int MODE>
; __device__ __forceinline__ void gemm_tile(const int ph, const int which, const int pm, const int pn) {
;     ...
;     STAGE(SB(0, 1), RB, bcolB, t + 2);
;     WAIT_V(6); BAR; MMA(1, 1, At, B1); BAR;
;     LDB(B0, 1, 0); SCHED; LDA(At, 1, 0); STAGE(SA(0, 1), RA, brow + HALF, t + 2);
;     WAIT_L(8); BAR; WAIT_L(0); MMA(0, 0, At, B0); BAR; SCHED;
;     LDB(B1, 1, 1); STAGE(SB(1, 0), RB, bcol, t + 3);
;     BAR; WAIT_L(0); MMA(0, 1, At, B1); BAR;
;     LDA(At, 1, 1); STAGE(SA(1, 0), RA, brow, t + 3);
	s_add_i32 s43, s17, s23
	v_readfirstlane_b32 s38, v142
	s_add_i32 s84, s43, 0x100
	s_mov_b32 m0, s38
	s_add_i32 s38, s11, s23
	v_readfirstlane_b32 s12, v143
	buffer_load_dwordx4 v136, s[68:71], s84 offen lds
	s_add_i32 s84, s38, 0x100
	s_mov_b32 m0, s12
	s_nop 0
	buffer_load_dwordx4 v136, s[68:71], s84 offen lds
	s_waitcnt vmcnt(6)
	s_barrier
	s_setprio 1
	v_mfma_f32_16x16x32_bf16 v[30:33], v[236:239], v[174:177], v[30:33]
	v_mfma_f32_16x16x32_bf16 v[26:29], v[244:247], v[174:177], v[26:29]
	v_mfma_f32_16x16x32_bf16 v[22:25], v[236:239], v[182:185], v[22:25]
	v_mfma_f32_16x16x32_bf16 v[18:21], v[244:247], v[182:185], v[18:21]
	v_mfma_f32_16x16x32_bf16 v[14:17], v[236:239], v[190:193], v[14:17]
	v_mfma_f32_16x16x32_bf16 v[10:13], v[244:247], v[190:193], v[10:13]
	v_mfma_f32_16x16x32_bf16 v[6:9], v[236:239], v[198:201], v[6:9]
	v_mfma_f32_16x16x32_bf16 v[2:5], v[244:247], v[198:201], v[2:5]
	v_mfma_f32_16x16x32_bf16 v[30:33], v[240:243], v[178:181], v[30:33]
	v_mfma_f32_16x16x32_bf16 v[26:29], v[248:251], v[178:181], v[26:29]
	v_mfma_f32_16x16x32_bf16 v[22:25], v[240:243], v[186:189], v[22:25]
	v_mfma_f32_16x16x32_bf16 v[18:21], v[248:251], v[186:189], v[18:21]
	v_mfma_f32_16x16x32_bf16 v[14:17], v[240:243], v[194:197], v[14:17]
	v_mfma_f32_16x16x32_bf16 v[10:13], v[248:251], v[194:197], v[10:13]
	v_mfma_f32_16x16x32_bf16 v[6:9], v[240:243], v[202:205], v[6:9]
	v_mfma_f32_16x16x32_bf16 v[2:5], v[248:251], v[202:205], v[2:5]
	s_setprio 0
	s_barrier
	ds_read_b128 v[158:161], v144
	ds_read_b128 v[162:165], v144 offset:1024
	ds_read_b128 v[166:169], v144 offset:2048
	ds_read_b128 v[170:173], v144 offset:3072
	v_readfirstlane_b32 s12, v145
	s_addk_i32 s26, 0x100
	s_mov_b32 m0, s12
	v_readfirstlane_b32 s12, v146
	ds_read_b128 v[174:177], v135 offset:32768
	ds_read_b128 v[178:181], v135 offset:33792
	ds_read_b128 v[182:185], v134 offset:32768
	ds_read_b128 v[186:189], v134 offset:33792
	ds_read_b128 v[190:193], v133 offset:32768
	ds_read_b128 v[194:197], v133 offset:33792
	ds_read_b128 v[198:201], v132 offset:32768
	ds_read_b128 v[202:205], v132 offset:33792
	buffer_load_dwordx4 v136, s[4:7], s26 offen lds
	s_addk_i32 s27, 0x100
	s_mov_b32 m0, s12
	s_nop 0
	buffer_load_dwordx4 v136, s[4:7], s27 offen lds
	s_waitcnt lgkmcnt(8)
	s_barrier
	s_waitcnt lgkmcnt(0)
	s_setprio 1
	v_mfma_f32_16x16x32_bf16 v[126:129], v[158:161], v[174:177], v[126:129]
	v_mfma_f32_16x16x32_bf16 v[122:125], v[166:169], v[174:177], v[122:125]
	v_mfma_f32_16x16x32_bf16 v[118:121], v[158:161], v[182:185], v[118:121]
	v_mfma_f32_16x16x32_bf16 v[114:117], v[166:169], v[182:185], v[114:117]
	v_mfma_f32_16x16x32_bf16 v[110:113], v[158:161], v[190:193], v[110:113]
	v_mfma_f32_16x16x32_bf16 v[106:109], v[166:169], v[190:193], v[106:109]
	v_mfma_f32_16x16x32_bf16 v[102:105], v[158:161], v[198:201], v[102:105]
	v_mfma_f32_16x16x32_bf16 v[98:101], v[166:169], v[198:201], v[98:101]
	v_mfma_f32_16x16x32_bf16 v[126:129], v[162:165], v[178:181], v[126:129]
	v_mfma_f32_16x16x32_bf16 v[122:125], v[170:173], v[178:181], v[122:125]
	v_mfma_f32_16x16x32_bf16 v[118:121], v[162:165], v[186:189], v[118:121]
	v_mfma_f32_16x16x32_bf16 v[114:117], v[170:173], v[186:189], v[114:117]
	v_mfma_f32_16x16x32_bf16 v[110:113], v[162:165], v[194:197], v[110:113]
	v_mfma_f32_16x16x32_bf16 v[106:109], v[170:173], v[194:197], v[106:109]
	v_mfma_f32_16x16x32_bf16 v[102:105], v[162:165], v[202:205], v[102:105]
	v_mfma_f32_16x16x32_bf16 v[98:101], v[170:173], v[202:205], v[98:101]
	s_setprio 0
	s_barrier
	v_readfirstlane_b32 s12, v147
	s_addk_i32 s28, 0x180
	s_mov_b32 m0, s12
	v_readfirstlane_b32 s12, v148
	ds_read_b128 v[236:239], v138
	ds_read_b128 v[240:243], v138 offset:1024
	ds_read_b128 v[244:247], v138 offset:2048
	ds_read_b128 v[248:251], v138 offset:3072
	buffer_load_dwordx4 v136, s[68:71], s28 offen lds
	s_addk_i32 s51, 0x180
	s_mov_b32 m0, s12
	s_nop 0
	buffer_load_dwordx4 v136, s[68:71], s51 offen lds
	s_barrier
	s_waitcnt lgkmcnt(0)
	s_setprio 1
	v_mfma_f32_16x16x32_bf16 v[94:97], v[236:239], v[174:177], v[94:97]
	v_mfma_f32_16x16x32_bf16 v[90:93], v[244:247], v[174:177], v[90:93]
	v_mfma_f32_16x16x32_bf16 v[86:89], v[236:239], v[182:185], v[86:89]
	v_mfma_f32_16x16x32_bf16 v[82:85], v[244:247], v[182:185], v[82:85]
	v_mfma_f32_16x16x32_bf16 v[78:81], v[236:239], v[190:193], v[78:81]
	v_mfma_f32_16x16x32_bf16 v[74:77], v[244:247], v[190:193], v[74:77]
	v_mfma_f32_16x16x32_bf16 v[70:73], v[236:239], v[198:201], v[70:73]
	v_mfma_f32_16x16x32_bf16 v[66:69], v[244:247], v[198:201], v[66:69]
	v_mfma_f32_16x16x32_bf16 v[94:97], v[240:243], v[178:181], v[94:97]
	v_mfma_f32_16x16x32_bf16 v[90:93], v[248:251], v[178:181], v[90:93]
	v_mfma_f32_16x16x32_bf16 v[86:89], v[240:243], v[186:189], v[86:89]
	v_mfma_f32_16x16x32_bf16 v[82:85], v[248:251], v[186:189], v[82:85]
	v_mfma_f32_16x16x32_bf16 v[78:81], v[240:243], v[194:197], v[78:81]
	v_mfma_f32_16x16x32_bf16 v[74:77], v[248:251], v[194:197], v[74:77]
	v_mfma_f32_16x16x32_bf16 v[70:73], v[240:243], v[202:205], v[70:73]
	v_mfma_f32_16x16x32_bf16 v[66:69], v[248:251], v[202:205], v[66:69]
	s_setprio 0
	v_readfirstlane_b32 s12, v149
	s_addk_i32 s50, 0x180
	s_mov_b32 m0, s12
	v_readfirstlane_b32 s12, v150
	s_barrier
	ds_read_b128 v[174:177], v135 offset:49152
	ds_read_b128 v[178:181], v135 offset:50176
	ds_read_b128 v[182:185], v134 offset:49152
	ds_read_b128 v[186:189], v134 offset:50176
	ds_read_b128 v[190:193], v133 offset:49152
	ds_read_b128 v[194:197], v133 offset:50176
	ds_read_b128 v[198:201], v132 offset:49152
	ds_read_b128 v[202:205], v132 offset:50176
	buffer_load_dwordx4 v136, s[4:7], s50 offen lds
	s_addk_i32 s29, 0x180
	s_mov_b32 m0, s12
	s_nop 0
	buffer_load_dwordx4 v136, s[4:7], s29 offen lds
	s_barrier
; #define WAIT_V(n) asm volatile("s_waitcnt vmcnt(" #n ")" ::: "memory")
; #define WAIT_L(n) asm volatile("s_waitcnt lgkmcnt(" #n ")" ::: "memory")
; #define BAR __builtin_amdgcn_s_barrier()
; #define SCHED __builtin_amdgcn_sched_barrier(0)
; template <int MODE>
; __device__ __forceinline__ void gemm_tile(const int ph, const int which, const int pm, const int pn) {
;     ...
;     BAR; WAIT_L(0); MMA(1, 0, At, B0); BAR; SCHED;
;     STAGE(SB(1, 1), RB, bcolB, t + 3);
;     WAIT_V(6); BAR; MMA(1, 1, At, B1); BAR;
;   }
;   {
;     LDB(B0, 0, 0); LDA(At, 0, 0); STAGE(SA(1, 1), RA, brow + HALF, nt - 1);
;     BAR; WAIT_L(0); MMA(0, 0, At, B0); BAR;
;     LDB(B1, 0, 1); BAR; WAIT_L(0); MMA(0, 1, At, B1); BAR;
	s_waitcnt lgkmcnt(0)
	s_setprio 1
	v_mfma_f32_16x16x32_bf16 v[62:65], v[158:161], v[174:177], v[62:65]
	v_mfma_f32_16x16x32_bf16 v[58:61], v[166:169], v[174:177], v[58:61]
	v_mfma_f32_16x16x32_bf16 v[54:57], v[158:161], v[182:185], v[54:57]
	v_mfma_f32_16x16x32_bf16 v[50:53], v[166:169], v[182:185], v[50:53]
	v_mfma_f32_16x16x32_bf16 v[46:49], v[158:161], v[190:193], v[46:49]
	v_mfma_f32_16x16x32_bf16 v[42:45], v[166:169], v[190:193], v[42:45]
	v_mfma_f32_16x16x32_bf16 v[38:41], v[158:161], v[198:201], v[38:41]
	v_mfma_f32_16x16x32_bf16 v[34:37], v[166:169], v[198:201], v[34:37]
	v_mfma_f32_16x16x32_bf16 v[62:65], v[162:165], v[178:181], v[62:65]
	v_mfma_f32_16x16x32_bf16 v[58:61], v[170:173], v[178:181], v[58:61]
	v_mfma_f32_16x16x32_bf16 v[54:57], v[162:165], v[186:189], v[54:57]
	v_mfma_f32_16x16x32_bf16 v[50:53], v[170:173], v[186:189], v[50:53]
	v_mfma_f32_16x16x32_bf16 v[46:49], v[162:165], v[194:197], v[46:49]
	v_mfma_f32_16x16x32_bf16 v[42:45], v[170:173], v[194:197], v[42:45]
	v_mfma_f32_16x16x32_bf16 v[38:41], v[162:165], v[202:205], v[38:41]
	v_mfma_f32_16x16x32_bf16 v[34:37], v[170:173], v[202:205], v[34:37]
	s_setprio 0
	s_barrier
	v_readfirstlane_b32 s12, v152
	s_addk_i32 s43, 0x180
	s_mov_b32 m0, s12
	v_readfirstlane_b32 s12, v154
	buffer_load_dwordx4 v136, s[68:71], s43 offen lds
	s_addk_i32 s38, 0x180
	s_mov_b32 m0, s12
	s_nop 0
	buffer_load_dwordx4 v136, s[68:71], s38 offen lds
	s_waitcnt vmcnt(6)
	s_barrier
	s_setprio 1
	v_mfma_f32_16x16x32_bf16 v[30:33], v[236:239], v[174:177], v[30:33]
	v_mfma_f32_16x16x32_bf16 v[26:29], v[244:247], v[174:177], v[26:29]
	v_mfma_f32_16x16x32_bf16 v[22:25], v[236:239], v[182:185], v[22:25]
	v_mfma_f32_16x16x32_bf16 v[18:21], v[244:247], v[182:185], v[18:21]
	v_mfma_f32_16x16x32_bf16 v[14:17], v[236:239], v[190:193], v[14:17]
	v_mfma_f32_16x16x32_bf16 v[10:13], v[244:247], v[190:193], v[10:13]
	v_mfma_f32_16x16x32_bf16 v[6:9], v[236:239], v[198:201], v[6:9]
	v_mfma_f32_16x16x32_bf16 v[2:5], v[244:247], v[198:201], v[2:5]
	v_mfma_f32_16x16x32_bf16 v[30:33], v[240:243], v[178:181], v[30:33]
	v_mfma_f32_16x16x32_bf16 v[26:29], v[248:251], v[178:181], v[26:29]
	v_mfma_f32_16x16x32_bf16 v[22:25], v[240:243], v[186:189], v[22:25]
	v_mfma_f32_16x16x32_bf16 v[18:21], v[248:251], v[186:189], v[18:21]
	v_mfma_f32_16x16x32_bf16 v[14:17], v[240:243], v[194:197], v[14:17]
	v_mfma_f32_16x16x32_bf16 v[10:13], v[248:251], v[194:197], v[10:13]
	v_mfma_f32_16x16x32_bf16 v[6:9], v[240:243], v[202:205], v[6:9]
	v_mfma_f32_16x16x32_bf16 v[2:5], v[248:251], v[202:205], v[2:5]
	s_setprio 0
	s_addk_i32 s23, 0x100
	s_cmp_lt_u32 s25, s2
	s_barrier
	s_cbranch_scc1 .LBB0_540
	s_add_i32 s2, s24, s9
	s_lshl_b32 s2, s2, 1
	v_readfirstlane_b32 s3, v153
	s_addk_i32 s2, 0xff80
	s_mov_b32 s6, s70
	s_mov_b32 s7, s71
	s_mov_b32 m0, s3
	v_readfirstlane_b32 s3, v151
	ds_read_b128 v[140:143], v156
	ds_read_b128 v[146:149], v156 offset:1024
	ds_read_b128 v[158:161], v156 offset:2048
	ds_read_b128 v[162:165], v156 offset:3072
	ds_read_b128 v[166:169], v135
	ds_read_b128 v[170:173], v135 offset:1024
	ds_read_b128 v[174:177], v134
	ds_read_b128 v[178:181], v134 offset:1024
	ds_read_b128 v[182:185], v133
	ds_read_b128 v[186:189], v133 offset:1024
	ds_read_b128 v[190:193], v132
	ds_read_b128 v[194:197], v132 offset:1024
	buffer_load_dwordx4 v136, s[4:7], s2 offen lds
	s_add_i32 s2, s2, s8
	s_mov_b32 m0, s3
	s_nop 0
	buffer_load_dwordx4 v136, s[4:7], s2 offen lds
	s_barrier
	s_waitcnt lgkmcnt(0)
	s_setprio 1
	v_mfma_f32_16x16x32_bf16 v[126:129], v[140:143], v[166:169], v[126:129]
	v_mfma_f32_16x16x32_bf16 v[122:125], v[158:161], v[166:169], v[122:125]
	v_mfma_f32_16x16x32_bf16 v[110:113], v[140:143], v[182:185], v[110:113]
	v_mfma_f32_16x16x32_bf16 v[106:109], v[158:161], v[182:185], v[106:109]
	v_mfma_f32_16x16x32_bf16 v[126:129], v[146:149], v[170:173], v[126:129]
	v_mfma_f32_16x16x32_bf16 v[122:125], v[162:165], v[170:173], v[122:125]
	v_mfma_f32_16x16x32_bf16 v[118:121], v[140:143], v[174:177], v[118:121]
	v_mfma_f32_16x16x32_bf16 v[114:117], v[158:161], v[174:177], v[114:117]
	v_mfma_f32_16x16x32_bf16 v[110:113], v[146:149], v[186:189], v[110:113]
	v_mfma_f32_16x16x32_bf16 v[106:109], v[162:165], v[186:189], v[106:109]
	v_mfma_f32_16x16x32_bf16 v[102:105], v[140:143], v[190:193], v[102:105]
	v_mfma_f32_16x16x32_bf16 v[98:101], v[158:161], v[190:193], v[98:101]
	v_mfma_f32_16x16x32_bf16 v[150:153], v[146:149], v[178:181], v[118:121]
	v_mfma_f32_16x16x32_bf16 v[198:201], v[162:165], v[178:181], v[114:117]
	v_mfma_f32_16x16x32_bf16 v[202:205], v[146:149], v[194:197], v[102:105]
	v_mfma_f32_16x16x32_bf16 v[236:239], v[162:165], v[194:197], v[98:101]
	s_setprio 0
	s_barrier
	s_nop 0
	ds_read_b128 v[98:101], v155
	ds_read_b128 v[102:105], v155 offset:1024
	ds_read_b128 v[114:117], v155 offset:2048
	ds_read_b128 v[118:121], v155 offset:3072
	s_barrier
	s_waitcnt lgkmcnt(0)
	s_setprio 1
	v_mfma_f32_16x16x32_bf16 v[94:97], v[98:101], v[166:169], v[94:97]
	v_mfma_f32_16x16x32_bf16 v[90:93], v[114:117], v[166:169], v[90:93]
	v_mfma_f32_16x16x32_bf16 v[78:81], v[98:101], v[182:185], v[78:81]
	v_mfma_f32_16x16x32_bf16 v[74:77], v[114:117], v[182:185], v[74:77]
	v_mfma_f32_16x16x32_bf16 v[70:73], v[98:101], v[190:193], v[70:73]
	v_mfma_f32_16x16x32_bf16 v[66:69], v[114:117], v[190:193], v[66:69]
	v_mfma_f32_16x16x32_bf16 v[94:97], v[102:105], v[170:173], v[94:97]
	v_mfma_f32_16x16x32_bf16 v[90:93], v[118:121], v[170:173], v[90:93]
	v_mfma_f32_16x16x32_bf16 v[86:89], v[98:101], v[174:177], v[86:89]
	v_mfma_f32_16x16x32_bf16 v[82:85], v[114:117], v[174:177], v[82:85]
	v_mfma_f32_16x16x32_bf16 v[78:81], v[102:105], v[186:189], v[78:81]
	v_mfma_f32_16x16x32_bf16 v[74:77], v[118:121], v[186:189], v[74:77]
	v_mfma_f32_16x16x32_bf16 v[70:73], v[102:105], v[194:197], v[70:73]
	v_mfma_f32_16x16x32_bf16 v[66:69], v[118:121], v[194:197], v[66:69]
	v_mfma_f32_16x16x32_bf16 v[154:157], v[102:105], v[178:181], v[86:89]
	v_mfma_f32_16x16x32_bf16 v[166:169], v[118:121], v[178:181], v[82:85]
	s_setprio 0
	s_barrier
; #define WAIT_V(n) asm volatile("s_waitcnt vmcnt(" #n ")" ::: "memory")
; #define WAIT_L(n) asm volatile("s_waitcnt lgkmcnt(" #n ")" ::: "memory")
; #define BAR __builtin_amdgcn_s_barrier()
; template <int MODE>
; __device__ __forceinline__ void gemm_tile(const int ph, const int which, const int pm, const int pn) {
;     ...
;     LDA(At, 0, 1); WAIT_V(4); BAR; WAIT_L(0); MMA(1, 0, At, B0); MMA(1, 1, At, B1); BAR;
;   }
;   {
;     LDB(B0, 1, 0); LDA(At, 1, 0); WAIT_V(2); BAR; WAIT_L(0); MMA(0, 0, At, B0); BAR;
	s_nop 0
	ds_read_b128 v[82:85], v135 offset:16384
	ds_read_b128 v[86:89], v135 offset:17408
	ds_read_b128 v[170:173], v134 offset:16384
	ds_read_b128 v[174:177], v134 offset:17408
	ds_read_b128 v[178:181], v133 offset:16384
	ds_read_b128 v[182:185], v133 offset:17408
	ds_read_b128 v[186:189], v132 offset:16384
	ds_read_b128 v[190:193], v132 offset:17408
	s_waitcnt vmcnt(4)
	s_barrier
	s_waitcnt lgkmcnt(0)
	s_setprio 1
	v_mfma_f32_16x16x32_bf16 v[62:65], v[140:143], v[82:85], v[62:65]
	v_mfma_f32_16x16x32_bf16 v[46:49], v[140:143], v[178:181], v[46:49]
	v_mfma_f32_16x16x32_bf16 v[42:45], v[158:161], v[178:181], v[42:45]
	v_mfma_f32_16x16x32_bf16 v[62:65], v[146:149], v[86:89], v[62:65]
	v_mfma_f32_16x16x32_bf16 v[58:61], v[158:161], v[82:85], v[58:61]
	v_mfma_f32_16x16x32_bf16 v[54:57], v[140:143], v[170:173], v[54:57]
	v_mfma_f32_16x16x32_bf16 v[50:53], v[158:161], v[170:173], v[50:53]
	v_mfma_f32_16x16x32_bf16 v[46:49], v[146:149], v[182:185], v[46:49]
	v_mfma_f32_16x16x32_bf16 v[42:45], v[162:165], v[182:185], v[42:45]
	v_mfma_f32_16x16x32_bf16 v[38:41], v[140:143], v[186:189], v[38:41]
	v_mfma_f32_16x16x32_bf16 v[34:37], v[158:161], v[186:189], v[34:37]
	v_mfma_f32_16x16x32_bf16 v[194:197], v[162:165], v[86:89], v[58:61]
	v_mfma_f32_16x16x32_bf16 v[240:243], v[146:149], v[174:177], v[54:57]
	v_mfma_f32_16x16x32_bf16 v[244:247], v[162:165], v[174:177], v[50:53]
	v_mfma_f32_16x16x32_bf16 v[140:143], v[146:149], v[190:193], v[38:41]
	v_mfma_f32_16x16x32_bf16 v[146:149], v[162:165], v[190:193], v[34:37]
	s_setprio 0
	s_setprio 1
	v_mfma_f32_16x16x32_bf16 v[30:33], v[98:101], v[82:85], v[30:33]
	v_mfma_f32_16x16x32_bf16 v[26:29], v[114:117], v[82:85], v[26:29]
	v_mfma_f32_16x16x32_bf16 v[14:17], v[98:101], v[178:181], v[14:17]
	v_mfma_f32_16x16x32_bf16 v[10:13], v[114:117], v[178:181], v[10:13]
	v_mfma_f32_16x16x32_bf16 v[30:33], v[102:105], v[86:89], v[30:33]
	v_mfma_f32_16x16x32_bf16 v[26:29], v[118:121], v[86:89], v[26:29]
	v_mfma_f32_16x16x32_bf16 v[22:25], v[98:101], v[170:173], v[22:25]
	v_mfma_f32_16x16x32_bf16 v[18:21], v[114:117], v[170:173], v[18:21]
	v_mfma_f32_16x16x32_bf16 v[14:17], v[102:105], v[182:185], v[14:17]
	v_mfma_f32_16x16x32_bf16 v[10:13], v[118:121], v[182:185], v[10:13]
	v_mfma_f32_16x16x32_bf16 v[6:9], v[98:101], v[186:189], v[6:9]
	v_mfma_f32_16x16x32_bf16 v[2:5], v[114:117], v[186:189], v[2:5]
	v_mfma_f32_16x16x32_bf16 v[158:161], v[102:105], v[174:177], v[22:25]
	v_mfma_f32_16x16x32_bf16 v[162:165], v[118:121], v[174:177], v[18:21]
	v_mfma_f32_16x16x32_bf16 v[170:173], v[102:105], v[190:193], v[6:9]
	v_mfma_f32_16x16x32_bf16 v[174:177], v[118:121], v[190:193], v[2:5]
	s_setprio 0
	s_barrier
	s_nop 1
	ds_read_b128 v[2:5], v144
	ds_read_b128 v[6:9], v144 offset:1024
	ds_read_b128 v[178:181], v144 offset:2048
	ds_read_b128 v[182:185], v144 offset:3072
	ds_read_b128 v[18:21], v135 offset:32768
	ds_read_b128 v[22:25], v135 offset:33792
	ds_read_b128 v[34:37], v134 offset:32768
	ds_read_b128 v[38:41], v134 offset:33792
	ds_read_b128 v[58:61], v133 offset:32768
	ds_read_b128 v[186:189], v133 offset:33792
	ds_read_b128 v[190:193], v132 offset:32768
	ds_read_b128 v[248:251], v132 offset:33792
	s_waitcnt vmcnt(2)
	s_barrier
	s_waitcnt lgkmcnt(0)
	s_setprio 1
	v_mfma_f32_16x16x32_bf16 v[50:53], v[2:5], v[18:21], v[126:129]
	v_mfma_f32_16x16x32_bf16 v[114:117], v[6:9], v[22:25], v[50:53]
	v_mfma_f32_16x16x32_bf16 v[50:53], v[178:181], v[18:21], v[122:125]
	v_mfma_f32_16x16x32_bf16 v[118:121], v[182:185], v[22:25], v[50:53]
	v_mfma_f32_16x16x32_bf16 v[50:53], v[2:5], v[34:37], v[150:153]
	v_mfma_f32_16x16x32_bf16 v[98:101], v[6:9], v[38:41], v[50:53]
	v_mfma_f32_16x16x32_bf16 v[50:53], v[178:181], v[34:37], v[198:201]
	v_mfma_f32_16x16x32_bf16 v[102:105], v[182:185], v[38:41], v[50:53]
	v_mfma_f32_16x16x32_bf16 v[50:53], v[2:5], v[58:61], v[110:113]
	v_mfma_f32_16x16x32_bf16 v[82:85], v[6:9], v[186:189], v[50:53]
	v_mfma_f32_16x16x32_bf16 v[50:53], v[178:181], v[58:61], v[106:109]
	v_mfma_f32_16x16x32_bf16 v[86:89], v[182:185], v[186:189], v[50:53]
	v_mfma_f32_16x16x32_bf16 v[50:53], v[2:5], v[190:193], v[202:205]
	v_mfma_f32_16x16x32_bf16 v[54:57], v[178:181], v[190:193], v[236:239]
	v_mfma_f32_16x16x32_bf16 v[50:53], v[6:9], v[248:251], v[50:53]
	v_mfma_f32_16x16x32_bf16 v[54:57], v[182:185], v[248:251], v[54:57]
	s_setprio 0
	s_barrier
; #define WAIT_V(n) asm volatile("s_waitcnt vmcnt(" #n ")" ::: "memory")
; #define WAIT_L(n) asm volatile("s_waitcnt lgkmcnt(" #n ")" ::: "memory")
; #define BAR __builtin_amdgcn_s_barrier()
; template <int MODE>
; __device__ __forceinline__ void gemm_tile(const int ph, const int which, const int pm, const int pn) {
;     ...
;     LDB(B1, 1, 1); WAIT_V(0); BAR; WAIT_L(0); MMA(0, 1, At, B1); BAR;
;     LDA(At, 1, 1); BAR; WAIT_L(0); MMA(1, 0, At, B0); MMA(1, 1, At, B1); BAR;
;   }
;   if (wr == 0) BAR;
	ds_read_b128 v[150:153], v138
	ds_read_b128 v[198:201], v138 offset:1024
	ds_read_b128 v[202:205], v138 offset:2048
	ds_read_b128 v[136:139], v138 offset:3072
	s_waitcnt vmcnt(0)
	s_barrier
	s_waitcnt lgkmcnt(0)
	s_setprio 1
	v_mfma_f32_16x16x32_bf16 v[94:97], v[150:153], v[18:21], v[94:97]
	v_mfma_f32_16x16x32_bf16 v[18:21], v[202:205], v[18:21], v[90:93]
	v_mfma_f32_16x16x32_bf16 v[126:129], v[136:139], v[22:25], v[18:21]
	v_mfma_f32_16x16x32_bf16 v[18:21], v[150:153], v[34:37], v[154:157]
	v_mfma_f32_16x16x32_bf16 v[106:109], v[198:201], v[38:41], v[18:21]
	v_mfma_f32_16x16x32_bf16 v[18:21], v[202:205], v[34:37], v[166:169]
	v_mfma_f32_16x16x32_bf16 v[110:113], v[136:139], v[38:41], v[18:21]
	v_mfma_f32_16x16x32_bf16 v[18:21], v[150:153], v[58:61], v[78:81]
	v_mfma_f32_16x16x32_bf16 v[90:93], v[198:201], v[186:189], v[18:21]
	v_mfma_f32_16x16x32_bf16 v[18:21], v[202:205], v[58:61], v[74:77]
	v_mfma_f32_16x16x32_bf16 v[122:125], v[198:201], v[22:25], v[94:97]
	v_mfma_f32_16x16x32_bf16 v[94:97], v[136:139], v[186:189], v[18:21]
	v_mfma_f32_16x16x32_bf16 v[18:21], v[150:153], v[190:193], v[70:73]
	v_mfma_f32_16x16x32_bf16 v[74:77], v[198:201], v[248:251], v[18:21]
	v_mfma_f32_16x16x32_bf16 v[18:21], v[202:205], v[190:193], v[66:69]
	v_mfma_f32_16x16x32_bf16 v[78:81], v[136:139], v[248:251], v[18:21]
	s_setprio 0
	s_barrier
	ds_read_b128 v[70:73], v135 offset:49152
	ds_read_b128 v[154:157], v135 offset:50176
	ds_read_b128 v[166:169], v134 offset:49152
	ds_read_b128 v[186:189], v134 offset:50176
	ds_read_b128 v[190:193], v133 offset:49152
	ds_read_b128 v[236:239], v133 offset:50176
	ds_read_b128 v[248:251], v132 offset:49152
	ds_read_b128 v[132:135], v132 offset:50176
	s_barrier
	s_waitcnt lgkmcnt(0)
	s_setprio 1
	v_mfma_f32_16x16x32_bf16 v[18:21], v[2:5], v[70:73], v[62:65]
	v_mfma_f32_16x16x32_bf16 v[58:61], v[6:9], v[154:157], v[18:21]
	v_mfma_f32_16x16x32_bf16 v[18:21], v[178:181], v[70:73], v[194:197]
	v_mfma_f32_16x16x32_bf16 v[62:65], v[182:185], v[154:157], v[18:21]
	v_mfma_f32_16x16x32_bf16 v[18:21], v[2:5], v[166:169], v[240:243]
	v_mfma_f32_16x16x32_bf16 v[34:37], v[6:9], v[186:189], v[18:21]
	v_mfma_f32_16x16x32_bf16 v[18:21], v[178:181], v[166:169], v[244:247]
	v_mfma_f32_16x16x32_bf16 v[38:41], v[182:185], v[186:189], v[18:21]
	v_mfma_f32_16x16x32_bf16 v[18:21], v[2:5], v[190:193], v[46:49]
	v_mfma_f32_16x16x32_bf16 v[2:5], v[2:5], v[248:251], v[140:143]
	v_mfma_f32_16x16x32_bf16 v[18:21], v[6:9], v[236:239], v[18:21]
	v_mfma_f32_16x16x32_bf16 v[22:25], v[178:181], v[190:193], v[42:45]
	v_mfma_f32_16x16x32_bf16 v[2:5], v[6:9], v[132:135], v[2:5]
	v_mfma_f32_16x16x32_bf16 v[6:9], v[178:181], v[248:251], v[146:149]
	v_mfma_f32_16x16x32_bf16 v[22:25], v[182:185], v[236:239], v[22:25]
	v_mfma_f32_16x16x32_bf16 v[6:9], v[182:185], v[132:135], v[6:9]
	s_setprio 0
	s_setprio 1
	v_mfma_f32_16x16x32_bf16 v[26:29], v[202:205], v[70:73], v[26:29]
	v_mfma_f32_16x16x32_bf16 v[30:33], v[150:153], v[70:73], v[30:33]
	v_mfma_f32_16x16x32_bf16 v[70:73], v[136:139], v[154:157], v[26:29]
	v_mfma_f32_16x16x32_bf16 v[26:29], v[150:153], v[166:169], v[158:161]
	v_mfma_f32_16x16x32_bf16 v[42:45], v[198:201], v[186:189], v[26:29]
	v_mfma_f32_16x16x32_bf16 v[26:29], v[202:205], v[166:169], v[162:165]
	v_mfma_f32_16x16x32_bf16 v[14:17], v[150:153], v[190:193], v[14:17]
	v_mfma_f32_16x16x32_bf16 v[10:13], v[202:205], v[190:193], v[10:13]
	v_mfma_f32_16x16x32_bf16 v[66:69], v[198:201], v[154:157], v[30:33]
	v_mfma_f32_16x16x32_bf16 v[46:49], v[136:139], v[186:189], v[26:29]
	v_mfma_f32_16x16x32_bf16 v[26:29], v[198:201], v[236:239], v[14:17]
	v_mfma_f32_16x16x32_bf16 v[30:33], v[136:139], v[236:239], v[10:13]
	v_mfma_f32_16x16x32_bf16 v[10:13], v[150:153], v[248:251], v[170:173]
	v_mfma_f32_16x16x32_bf16 v[14:17], v[202:205], v[248:251], v[174:177]
	v_mfma_f32_16x16x32_bf16 v[10:13], v[198:201], v[132:135], v[10:13]
	v_mfma_f32_16x16x32_bf16 v[14:17], v[136:139], v[132:135], v[14:17]
	s_setprio 0
	s_movk_i32 s2, 0x100
	v_cmp_gt_u32_e32 vcc, s2, v0
	s_barrier
	s_and_saveexec_b64 s[2:3], vcc
	s_cbranch_execz .LBB0_543
	s_barrier
